# p4 + M1 output stores write full 128B lines (B-tile column map so a wave's two column groups are adjacent + DPP lane exchange in the epilogue)
# speedup vs baseline: 1.0028x; 1.0028x over previous
.LBB0_1154:
	s_andn2_b64 vcc, exec, s[0:1]
	s_cbranch_vccnz .LBB0_1219
	s_mov_b64 s[100:101], 0x20000
	v_readlane_b32 s0, v254, 0
	v_readlane_b32 s1, v254, 1
	v_readlane_b32 s2, v254, 4
	v_mbcnt_lo_u32_b32 v0, -1, 0
	v_mbcnt_hi_u32_b32 v0, -1, v0
	s_waitcnt lgkmcnt(0)
	s_mov_b32 s15, s80
	v_readlane_b32 s2, v254, 5
	v_readlane_b32 s3, v254, 6
	s_waitcnt vmcnt(0)
	v_mov_b64_e32 v[2:3], s[0:1]
	s_load_dword s14, s[2:3], 0x0
	flat_load_dwordx2 v[140:141], v[2:3] offset:224
	v_mbcnt_lo_u32_b32 v0, -1, 0
	v_mbcnt_hi_u32_b32 v0, -1, v0
	s_cmpk_gt_i32 s15, 0x13ff
	v_add_u32_e32 v0, s81, v0
	s_nop 0
	v_readfirstlane_b32 s3, v0
	s_cbranch_scc1 .LBB0_1173
	v_bfe_i32 v2, v0, 27, 1
	v_lshlrev_b32_e32 v145, 4, v0
	v_lshrrev_b32_e32 v2, 22, v2
	v_add_u32_e32 v2, v145, v2
	v_and_b32_e32 v2, 0xfffffc00, v2
	v_sub_u32_e32 v2, v145, v2
	v_lshrrev_b32_e32 v3, 4, v2
	v_ashrrev_i32_e32 v4, 31, v0
	v_bitop3_b32 v2, v3, v2, 32 bitop3:0x6c
	v_lshrrev_b32_e32 v4, 26, v4
	v_ashrrev_i32_e32 v3, 31, v2
	v_add_u32_e32 v4, v0, v4
	v_lshrrev_b32_e32 v3, 26, v3
	v_ashrrev_i32_e32 v146, 6, v4
	s_mov_b64 s[0:1], 0x2200000
	v_add_u32_e32 v3, v2, v3
	v_lshlrev_b32_e32 v4, 3, v146
	s_waitcnt vmcnt(0) lgkmcnt(0)
	v_lshl_add_u64 v[130:131], v[140:141], 0, s[0:1]
	s_mov_b64 s[0:1], 0x8200000
	v_ashrrev_i32_e32 v144, 6, v3
	v_and_b32_e32 v4, -16, v4
	v_lshl_add_u64 v[132:133], v[140:141], 0, s[0:1]
	v_add_u32_e32 v4, v144, v4
	v_and_b32_e32 v5, 3, v144
	s_mov_b32 s0, 0xfffe0
	s_ashr_i32 s17, s15, 31
	v_and_or_b32 v5, v4, s0, v5
	s_lshr_b32 s0, s17, 29
	s_add_i32 s0, s15, s0
	s_ashr_i32 s4, s3, 6
	s_ashr_i32 s1, s0, 3
	s_and_b32 s0, s0, -8
	s_ashr_i32 s5, s3, 8
	s_lshl_b32 s16, s4, 10
	s_sub_i32 s0, s15, s0
	s_cmp_lt_i32 s0, 0
	s_movk_i32 s2, 0x281
	s_cselect_b32 s2, s2, 0x280
	s_mul_i32 s0, s0, s2
	s_add_i32 s0, s0, s1
	s_ashr_i32 s1, s0, 31
	s_lshr_b32 s1, s1, 24
	s_add_i32 s1, s0, s1
	s_ashr_i32 s2, s1, 8
	s_and_b32 s1, s1, 0xff00
	s_sub_i32 s0, s0, s1
	s_sext_i32_i16 s1, s0
	s_bfe_u32 s1, s1, 0x3001c
	s_add_i32 s1, s0, s1
	v_lshrrev_b32_e32 v6, 2, v4
	v_lshlrev_b32_e32 v7, 1, v4
	v_and_b32_e32 v3, 0xc0, v3
	s_lshl_b32 s6, s2, 3
	s_sext_i32_i16 s2, s1
	s_and_b32 s1, s1, 0xfff8
	v_and_b32_e32 v6, 4, v6
	v_and_b32_e32 v7, 24, v7
	v_sub_u32_e32 v2, v2, v3
	s_sub_i32 s0, s0, s1
	v_or3_b32 v5, v5, v6, v7
	v_lshlrev_b32_e32 v6, 5, v146
	v_ashrrev_i16_sdwa v2, v241, sext(v2) dst_sel:DWORD dst_unused:UNUSED_PAD src0_sel:DWORD src1_sel:BYTE_0
	s_lshr_b32 s2, s2, 3
	s_sext_i32_i16 s0, s0
	v_and_b32_e32 v6, 32, v6
	v_bfe_i32 v147, v2, 0, 16
	s_add_i32 s10, s6, s0
	s_bfe_i64 s[6:7], s[2:3], 0x100000
	v_add_lshl_u32 v2, v6, v147, 1
	s_lshl_b64 s[6:7], s[6:7], 20
	v_and_b32_e32 v7, 32, v5
	v_add_u32_e32 v5, v5, v7
	v_lshl_add_u32 v134, v5, 12, v2
	v_lshl_add_u64 v[148:149], v[130:131], 0, s[6:7]
	v_mov_b32_e32 v135, v1
	s_add_i32 s18, s16, 0
	v_lshl_add_u64 v[138:139], v[148:149], 0, v[134:135]
	s_add_i32 m0, s18, 0x10000
	v_lshl_add_u32 v136, v4, 12, v2
	s_ashr_i32 s11, s10, 31
	global_load_lds_dwordx4 v[138:139], off
	v_lshl_add_u64 v[142:143], v[138:139], 0, s[54:55]
	s_add_i32 m0, s18, 0x12000
	s_lshl_b64 s[0:1], s[10:11], 20
	global_load_lds_dwordx4 v[142:143], off
	v_lshl_add_u64 v[142:143], v[138:139], 0, s[100:101]
	s_add_i32 m0, s18, 0x14000
	v_lshl_add_u64 v[150:151], v[132:133], 0, s[0:1]
	global_load_lds_dwordx4 v[142:143], off
	v_lshl_add_u64 v[142:143], v[142:143], 0, s[54:55]
	s_add_i32 m0, s18, 0x16000
	v_mov_b32_e32 v137, v1
	global_load_lds_dwordx4 v[142:143], off
	v_lshl_add_u64 v[142:143], v[150:151], 0, v[136:137]
	s_mov_b32 m0, s18
	s_add_i32 s19, s18, 0x2000
	global_load_lds_dwordx4 v[142:143], off
	v_lshl_add_u64 v[152:153], v[142:143], 0, s[52:53]
	s_mov_b32 m0, s19
	s_add_i32 s20, s18, 0x4000
	global_load_lds_dwordx4 v[152:153], off
	v_lshl_add_u64 v[152:153], v[142:143], 0, s[54:55]
	s_mov_b32 m0, s20
	s_add_i32 s21, s18, 0x6000
	global_load_lds_dwordx4 v[152:153], off
	v_lshl_add_u64 v[152:153], v[142:143], 0, s[56:57]
	s_mov_b32 m0, s21
	s_cmp_eq_u32 s5, 1
	global_load_lds_dwordx4 v[152:153], off
	s_cselect_b64 s[0:1], -1, 0
	s_cmp_lg_u32 s5, 1
	s_cbranch_scc1 .LBB0_1158
	s_barrier
.LBB0_1158:
	v_lshl_add_u64 v[152:153], v[138:139], 0, s[62:63]
	s_add_i32 m0, s18, 0x18000
	s_waitcnt vmcnt(2)
	s_barrier
	global_load_lds_dwordx4 v[152:153], off
	v_lshl_add_u64 v[152:153], v[138:139], 0, s[66:67]
	s_add_i32 m0, s18, 0x1a000
	s_add_i32 s22, s18, 0x8000
	global_load_lds_dwordx4 v[152:153], off
	v_lshl_add_u64 v[152:153], v[142:143], 0, s[62:63]
	s_mov_b32 m0, s22
	s_add_i32 s23, s18, 0xa000
	global_load_lds_dwordx4 v[152:153], off
	v_lshl_add_u64 v[142:143], v[142:143], 0, s[64:65]
	s_mov_b32 m0, s23
	s_sext_i32_i16 s11, s2
	global_load_lds_dwordx4 v[142:143], off
	v_lshl_add_u64 v[142:143], v[138:139], 0, s[62:63]
	v_lshl_add_u64 v[142:143], v[142:143], 0, s[100:101]
	s_add_i32 m0, s18, 0x1c000
	v_lshl_add_u64 v[138:139], v[142:143], 0, s[54:55]
	global_load_lds_dwordx4 v[142:143], off
	s_add_i32 m0, s18, 0x1e000
	v_and_b32_e32 v142, 15, v0
	global_load_lds_dwordx4 v[138:139], off
	v_lshl_or_b32 v161, s5, 6, v142
	v_lshlrev_b32_e32 v153, 6, v161
	v_and_b32_e32 v154, 48, v0
	s_movk_i32 s2, 0x3c0
	v_lshlrev_b32_e32 v155, 2, v0
	v_and_or_b32 v143, v153, s2, v154
	s_lshl_b32 s2, s5, 13
	v_and_b32_e32 v155, 32, v155
	v_bitop3_b32 v156, v143, s2, v155 bitop3:0xde
	s_lshl_b32 s2, s4, 5
	s_mov_b64 s[6:7], 0x12200000
	s_and_b32 s5, s2, 0x60
	v_lshl_add_u64 v[138:139], v[140:141], 0, s[6:7]
	v_lshl_or_b32 v142, v142, 6, v154
	s_lshl_b32 s6, s5, 7
	v_bitop3_b32 v163, v142, s6, v155 bitop3:0xde
	v_and_b32_e32 v142, 48, v145
	v_mov_b32_e32 v143, v1
	v_lshrrev_b32_e32 v152, 1, v0
	s_lshl_b32 s6, s4, 1
	v_bfe_u32 v0, v0, 2, 4
	v_lshl_add_u64 v[140:141], v[140:141], 0, v[142:143]
	v_lshlrev_b32_e32 v142, 15, v146
	v_or_b32_e32 v166, s2, v0
	s_or_b32 s2, s6, 1
	v_and_b32_e32 v142, 0xffff0000, v142
	s_waitcnt vmcnt(0)
	s_lshl_b32 s4, s4, 11
	s_lshl_b32 s6, s2, 10
	v_readlane_b32 s7, v254, 11
	v_lshl_add_u32 v142, v144, 12, v142
	v_and_b32_e32 v143, 1, v146
	v_lshl_or_b32 v167, s2, 4, v0
	s_cmpk_lt_u32 s3, 0x100
	s_mov_b64 s[8:9], 0x3c800000
	v_add_u32_e32 v0, s7, v153
	v_lshl_or_b32 v142, v143, 6, v142
	s_cselect_b64 s[2:3], -1, 0
	s_ashr_i32 s24, s14, 31
	v_lshl_add_u64 v[140:141], v[140:141], 0, s[8:9]
	v_and_or_b32 v168, v152, 24, s5
	v_add_u32_e32 v168, s5, v168
	v_and_b32_e32 v171, 4, v152
	v_lshl_add_u32 v168, v171, 3, v168
	v_lshl_add_u32 v142, v147, 1, v142
	v_mov_b32_e32 v143, v1
	s_mov_b32 s25, 0
	v_add_u32_e32 v169, 0, v156
	v_add_u32_e32 v170, v0, v154
	s_add_i32 s26, s7, s4
	s_add_i32 s27, s7, s6
	s_barrier
	s_branch .LBB0_1161

.LBB0_1163:
	s_ashr_i32 s9, s8, 31
	s_lshl_b64 s[12:13], s[8:9], 20
	s_ashr_i32 s7, s6, 31
	v_lshl_add_u64 v[144:145], v[132:133], 0, s[12:13]
	s_lshl_b64 s[12:13], s[6:7], 20
	s_lshl_b32 s7, s10, 8
	v_add_u32_e32 v156, s7, v166
	v_ashrrev_i32_e32 v157, 31, v156
	v_lshlrev_b64 v[158:159], 6, v[156:157]
	v_add_u32_e32 v156, s7, v167
	v_ashrrev_i32_e32 v157, 31, v156
	v_lshl_add_u64 v[146:147], v[130:131], 0, s[12:13]
	v_lshlrev_b64 v[156:157], 6, v[156:157]
	v_cndmask_b32_e64 v153, v151, v145, s[4:5]
	v_cndmask_b32_e64 v0, v150, v144, s[4:5]
	v_cndmask_b32_e64 v155, v149, v147, s[4:5]
	v_cndmask_b32_e64 v152, v148, v146, s[4:5]
	v_lshl_add_u64 v[156:157], v[140:141], 0, v[156:157]
	v_lshl_add_u64 v[158:159], v[140:141], 0, v[158:159]
	v_lshl_add_u64 v[150:151], v[150:151], 0, s[66:67]
	v_lshl_add_u64 v[148:149], v[148:149], 0, s[72:73]
	s_mov_b32 s9, -2
	s_mov_b64 vcc, 0
	s_add_i32 s10, 0, 0x10000
	v_add_u32_e32 v154, s10, v163
	s_add_i32 s12, 0, 0x14000
	ds_read_b128 v[172:175], v154
	ds_read_b128 v[176:179], v154 offset:1024
	ds_read_b128 v[180:183], v154 offset:2048
	ds_read_b128 v[184:187], v154 offset:3072
	v_add_u32_e32 v154, s12, v163
	ds_read_b128 v[188:191], v154
	ds_read_b128 v[192:195], v154 offset:1024
	ds_read_b128 v[196:199], v154 offset:2048
	ds_read_b128 v[200:203], v154 offset:3072
	v_lshl_add_u64 v[164:165], v[150:151], 0, s[74:75]
	v_cndmask_b32_e32 v165, v165, v153, vcc
	v_cndmask_b32_e32 v164, v164, v0, vcc
	v_cndmask_b32_e32 v205, v149, v155, vcc
	v_cndmask_b32_e32 v204, v148, v152, vcc
	v_lshl_add_u64 v[206:207], v[150:151], 0, v[142:143]
	s_add_i32 m0, s18, 0xc000
	ds_read_b128 v[210:213], v169
	ds_read_b128 v[214:217], v169 offset:1024
	ds_read_b128 v[218:221], v169 offset:2048
	ds_read_b128 v[222:225], v169 offset:3072
	ds_read_b128 v[226:229], v169 offset:4096
	ds_read_b128 v[230:233], v169 offset:5120
	ds_read_b128 v[234:237], v169 offset:6144
	ds_read_b128 v[250:253], v169 offset:7168
	global_load_lds_dwordx4 v[206:207], off
	v_lshl_add_u64 v[206:207], v[206:207], 0, s[52:53]
	s_add_i32 m0, s18, 0xe000
	s_nop 0
	global_load_lds_dwordx4 v[206:207], off
	s_waitcnt vmcnt(24)
	s_waitcnt lgkmcnt(0)
	s_barrier
	s_setprio 1
	s_waitcnt lgkmcnt(0)
	v_mfma_f32_16x16x32_bf16 v[126:129], v[172:175], v[210:213], 0
	v_mfma_f32_16x16x32_bf16 v[122:125], v[180:183], v[210:213], 0
	v_mfma_f32_16x16x32_bf16 v[110:113], v[172:175], v[218:221], 0
	v_mfma_f32_16x16x32_bf16 v[106:109], v[180:183], v[218:221], 0
	v_mfma_f32_16x16x32_bf16 v[94:97], v[172:175], v[226:229], 0
	v_mfma_f32_16x16x32_bf16 v[90:93], v[180:183], v[226:229], 0
	v_mfma_f32_16x16x32_bf16 v[78:81], v[172:175], v[234:237], 0
	v_mfma_f32_16x16x32_bf16 v[74:77], v[180:183], v[234:237], 0
	v_mfma_f32_16x16x32_bf16 v[126:129], v[176:179], v[214:217], v[126:129]
	v_mfma_f32_16x16x32_bf16 v[122:125], v[184:187], v[214:217], v[122:125]
	v_mfma_f32_16x16x32_bf16 v[110:113], v[176:179], v[222:225], v[110:113]
	v_mfma_f32_16x16x32_bf16 v[106:109], v[184:187], v[222:225], v[106:109]
	v_mfma_f32_16x16x32_bf16 v[94:97], v[176:179], v[230:233], v[94:97]
	v_mfma_f32_16x16x32_bf16 v[90:93], v[184:187], v[230:233], v[90:93]
	v_mfma_f32_16x16x32_bf16 v[78:81], v[176:179], v[250:253], v[78:81]
	v_mfma_f32_16x16x32_bf16 v[74:77], v[184:187], v[250:253], v[74:77]
	s_setprio 0
	s_setprio 1
	v_mfma_f32_16x16x32_bf16 v[118:121], v[188:191], v[210:213], 0
	v_mfma_f32_16x16x32_bf16 v[114:117], v[196:199], v[210:213], 0
	v_mfma_f32_16x16x32_bf16 v[102:105], v[188:191], v[218:221], 0
	v_mfma_f32_16x16x32_bf16 v[98:101], v[196:199], v[218:221], 0
	v_mfma_f32_16x16x32_bf16 v[86:89], v[188:191], v[226:229], 0
	v_mfma_f32_16x16x32_bf16 v[82:85], v[196:199], v[226:229], 0
	v_mfma_f32_16x16x32_bf16 v[70:73], v[188:191], v[234:237], 0
	v_mfma_f32_16x16x32_bf16 v[66:69], v[196:199], v[234:237], 0
	v_mfma_f32_16x16x32_bf16 v[118:121], v[192:195], v[214:217], v[118:121]
	v_mfma_f32_16x16x32_bf16 v[114:117], v[200:203], v[214:217], v[114:117]
	v_mfma_f32_16x16x32_bf16 v[102:105], v[192:195], v[222:225], v[102:105]
	v_mfma_f32_16x16x32_bf16 v[98:101], v[200:203], v[222:225], v[98:101]
	v_mfma_f32_16x16x32_bf16 v[86:89], v[192:195], v[230:233], v[86:89]
	v_mfma_f32_16x16x32_bf16 v[82:85], v[200:203], v[230:233], v[82:85]
	v_mfma_f32_16x16x32_bf16 v[70:73], v[192:195], v[250:253], v[70:73]
	v_mfma_f32_16x16x32_bf16 v[66:69], v[200:203], v[250:253], v[66:69]
	s_setprio 0
	s_barrier
	s_add_i32 s10, s10, s16
	v_lshl_add_u64 v[204:205], v[204:205], 0, v[134:135]
	s_mov_b32 m0, s10
	ds_read_b128 v[210:213], v169 offset:16384
	ds_read_b128 v[214:217], v169 offset:17408
	ds_read_b128 v[218:221], v169 offset:18432
	ds_read_b128 v[222:225], v169 offset:19456
	ds_read_b128 v[226:229], v169 offset:20480
	ds_read_b128 v[230:233], v169 offset:21504
	ds_read_b128 v[234:237], v169 offset:22528
	ds_read_b128 v[250:253], v169 offset:23552
	global_load_lds_dwordx4 v[204:205], off
	v_lshl_add_u64 v[206:207], v[204:205], 0, s[54:55]
	s_add_i32 m0, s10, 0x2000
	s_add_i32 s10, s12, s16
	global_load_lds_dwordx4 v[206:207], off
	v_lshl_add_u64 v[206:207], v[204:205], 0, s[100:101]
	s_mov_b32 m0, s10
	v_lshl_add_u64 v[164:165], v[164:165], 0, v[136:137]
	global_load_lds_dwordx4 v[206:207], off
	v_lshl_add_u64 v[206:207], v[206:207], 0, s[54:55]
	s_add_i32 m0, s10, 0x2000
	s_nop 0
	global_load_lds_dwordx4 v[206:207], off
	s_mov_b32 m0, s18
	v_lshl_add_u64 v[206:207], v[164:165], 0, s[52:53]
	global_load_lds_dwordx4 v[164:165], off
	s_mov_b32 m0, s19
	s_nop 0
	global_load_lds_dwordx4 v[206:207], off
	s_waitcnt vmcnt(24)
	s_waitcnt lgkmcnt(0)
	s_barrier
	s_setprio 1
	s_waitcnt lgkmcnt(0)
	v_mfma_f32_16x16x32_bf16 v[62:65], v[172:175], v[210:213], 0
	v_mfma_f32_16x16x32_bf16 v[58:61], v[180:183], v[210:213], 0
	v_mfma_f32_16x16x32_bf16 v[46:49], v[172:175], v[218:221], 0
	v_mfma_f32_16x16x32_bf16 v[42:45], v[180:183], v[218:221], 0
	v_mfma_f32_16x16x32_bf16 v[30:33], v[172:175], v[226:229], 0
	v_mfma_f32_16x16x32_bf16 v[26:29], v[180:183], v[226:229], 0
	v_mfma_f32_16x16x32_bf16 v[14:17], v[172:175], v[234:237], 0
	v_mfma_f32_16x16x32_bf16 v[10:13], v[180:183], v[234:237], 0
	v_mfma_f32_16x16x32_bf16 v[62:65], v[176:179], v[214:217], v[62:65]
	v_mfma_f32_16x16x32_bf16 v[58:61], v[184:187], v[214:217], v[58:61]
	v_mfma_f32_16x16x32_bf16 v[46:49], v[176:179], v[222:225], v[46:49]
	v_mfma_f32_16x16x32_bf16 v[42:45], v[184:187], v[222:225], v[42:45]
	v_mfma_f32_16x16x32_bf16 v[30:33], v[176:179], v[230:233], v[30:33]
	v_mfma_f32_16x16x32_bf16 v[26:29], v[184:187], v[230:233], v[26:29]
	v_mfma_f32_16x16x32_bf16 v[14:17], v[176:179], v[250:253], v[14:17]
	v_mfma_f32_16x16x32_bf16 v[10:13], v[184:187], v[250:253], v[10:13]
	s_setprio 0
	s_setprio 1
	v_mfma_f32_16x16x32_bf16 v[54:57], v[188:191], v[210:213], 0
	v_mfma_f32_16x16x32_bf16 v[50:53], v[196:199], v[210:213], 0
	v_mfma_f32_16x16x32_bf16 v[38:41], v[188:191], v[218:221], 0
	v_mfma_f32_16x16x32_bf16 v[34:37], v[196:199], v[218:221], 0
	v_mfma_f32_16x16x32_bf16 v[22:25], v[188:191], v[226:229], 0
	v_mfma_f32_16x16x32_bf16 v[18:21], v[196:199], v[226:229], 0
	v_mfma_f32_16x16x32_bf16 v[2:5], v[188:191], v[234:237], 0
	v_mfma_f32_16x16x32_bf16 v[6:9], v[196:199], v[234:237], 0
	v_mfma_f32_16x16x32_bf16 v[54:57], v[192:195], v[214:217], v[54:57]
	v_mfma_f32_16x16x32_bf16 v[50:53], v[200:203], v[214:217], v[50:53]
	v_mfma_f32_16x16x32_bf16 v[38:41], v[192:195], v[222:225], v[38:41]
	v_mfma_f32_16x16x32_bf16 v[34:37], v[200:203], v[222:225], v[34:37]
	v_mfma_f32_16x16x32_bf16 v[22:25], v[192:195], v[230:233], v[22:25]
	v_mfma_f32_16x16x32_bf16 v[18:21], v[200:203], v[230:233], v[18:21]
	v_mfma_f32_16x16x32_bf16 v[2:5], v[192:195], v[250:253], v[2:5]
	v_mfma_f32_16x16x32_bf16 v[6:9], v[200:203], v[250:253], v[6:9]
	s_setprio 0
	s_barrier
	s_add_i32 s10, 0, 0x18000
	v_add_u32_e32 v154, s10, v163
	s_add_i32 s12, 0, 0x1c000
	ds_read_b128 v[172:175], v154
	ds_read_b128 v[176:179], v154 offset:1024
	ds_read_b128 v[180:183], v154 offset:2048
	ds_read_b128 v[184:187], v154 offset:3072
	v_add_u32_e32 v154, s12, v163
	ds_read_b128 v[188:191], v154
	ds_read_b128 v[192:195], v154 offset:1024
	ds_read_b128 v[196:199], v154 offset:2048
	ds_read_b128 v[200:203], v154 offset:3072
	s_mov_b32 m0, s20
	v_lshl_add_u64 v[206:207], v[164:165], 0, s[54:55]
	ds_read_b128 v[210:213], v169 offset:32768
	ds_read_b128 v[214:217], v169 offset:33792
	ds_read_b128 v[218:221], v169 offset:34816
	ds_read_b128 v[222:225], v169 offset:35840
	ds_read_b128 v[226:229], v169 offset:36864
	ds_read_b128 v[230:233], v169 offset:37888
	ds_read_b128 v[234:237], v169 offset:38912
	ds_read_b128 v[250:253], v169 offset:39936
	global_load_lds_dwordx4 v[206:207], off
	v_lshl_add_u64 v[206:207], v[164:165], 0, s[56:57]
	s_mov_b32 m0, s21
	s_nop 0
	global_load_lds_dwordx4 v[206:207], off
	s_waitcnt vmcnt(8)
	s_waitcnt lgkmcnt(0)
	s_barrier
	s_setprio 1
	s_waitcnt lgkmcnt(0)
	v_mfma_f32_16x16x32_bf16 v[126:129], v[172:175], v[210:213], v[126:129]
	v_mfma_f32_16x16x32_bf16 v[122:125], v[180:183], v[210:213], v[122:125]
	v_mfma_f32_16x16x32_bf16 v[110:113], v[172:175], v[218:221], v[110:113]
	v_mfma_f32_16x16x32_bf16 v[106:109], v[180:183], v[218:221], v[106:109]
	v_mfma_f32_16x16x32_bf16 v[94:97], v[172:175], v[226:229], v[94:97]
	v_mfma_f32_16x16x32_bf16 v[90:93], v[180:183], v[226:229], v[90:93]
	v_mfma_f32_16x16x32_bf16 v[78:81], v[172:175], v[234:237], v[78:81]
	v_mfma_f32_16x16x32_bf16 v[74:77], v[180:183], v[234:237], v[74:77]
	v_mfma_f32_16x16x32_bf16 v[126:129], v[176:179], v[214:217], v[126:129]
	v_mfma_f32_16x16x32_bf16 v[122:125], v[184:187], v[214:217], v[122:125]
	v_mfma_f32_16x16x32_bf16 v[110:113], v[176:179], v[222:225], v[110:113]
	v_mfma_f32_16x16x32_bf16 v[106:109], v[184:187], v[222:225], v[106:109]
	v_mfma_f32_16x16x32_bf16 v[94:97], v[176:179], v[230:233], v[94:97]
	v_mfma_f32_16x16x32_bf16 v[90:93], v[184:187], v[230:233], v[90:93]
	v_mfma_f32_16x16x32_bf16 v[78:81], v[176:179], v[250:253], v[78:81]
	v_mfma_f32_16x16x32_bf16 v[74:77], v[184:187], v[250:253], v[74:77]
	s_setprio 0
	s_setprio 1
	v_mfma_f32_16x16x32_bf16 v[118:121], v[188:191], v[210:213], v[118:121]
	v_mfma_f32_16x16x32_bf16 v[114:117], v[196:199], v[210:213], v[114:117]
	v_mfma_f32_16x16x32_bf16 v[102:105], v[188:191], v[218:221], v[102:105]
	v_mfma_f32_16x16x32_bf16 v[98:101], v[196:199], v[218:221], v[98:101]
	v_mfma_f32_16x16x32_bf16 v[86:89], v[188:191], v[226:229], v[86:89]
	v_mfma_f32_16x16x32_bf16 v[82:85], v[196:199], v[226:229], v[82:85]
	v_mfma_f32_16x16x32_bf16 v[70:73], v[188:191], v[234:237], v[70:73]
	v_mfma_f32_16x16x32_bf16 v[66:69], v[196:199], v[234:237], v[66:69]
	v_mfma_f32_16x16x32_bf16 v[118:121], v[192:195], v[214:217], v[118:121]
	v_mfma_f32_16x16x32_bf16 v[114:117], v[200:203], v[214:217], v[114:117]
	v_mfma_f32_16x16x32_bf16 v[102:105], v[192:195], v[222:225], v[102:105]
	v_mfma_f32_16x16x32_bf16 v[98:101], v[200:203], v[222:225], v[98:101]
	v_mfma_f32_16x16x32_bf16 v[86:89], v[192:195], v[230:233], v[86:89]
	v_mfma_f32_16x16x32_bf16 v[82:85], v[200:203], v[230:233], v[82:85]
	v_mfma_f32_16x16x32_bf16 v[70:73], v[192:195], v[250:253], v[70:73]
	v_mfma_f32_16x16x32_bf16 v[66:69], v[200:203], v[250:253], v[66:69]
	s_setprio 0
	s_barrier
	s_add_i32 s10, s10, s16
	v_lshl_add_u64 v[206:207], v[204:205], 0, s[62:63]
	s_mov_b32 m0, s10
	ds_read_b128 v[210:213], v169 offset:49152
	ds_read_b128 v[214:217], v169 offset:50176
	ds_read_b128 v[218:221], v169 offset:51200
	ds_read_b128 v[222:225], v169 offset:52224
	ds_read_b128 v[226:229], v169 offset:53248
	ds_read_b128 v[230:233], v169 offset:54272
	ds_read_b128 v[234:237], v169 offset:55296
	ds_read_b128 v[250:253], v169 offset:56320
	global_load_lds_dwordx4 v[206:207], off
	v_lshl_add_u64 v[206:207], v[204:205], 0, s[66:67]
	s_add_i32 m0, s10, 0x2000
	s_add_i32 s10, s12, s16
	global_load_lds_dwordx4 v[206:207], off
	v_lshl_add_u64 v[206:207], v[204:205], 0, s[62:63]
	v_lshl_add_u64 v[206:207], v[206:207], 0, s[100:101]
	s_mov_b32 m0, s10
	v_lshl_add_u64 v[204:205], v[206:207], 0, s[54:55]
	global_load_lds_dwordx4 v[206:207], off
	s_add_i32 m0, s10, 0x2000
	s_nop 0
	global_load_lds_dwordx4 v[204:205], off
	v_lshl_add_u64 v[204:205], v[164:165], 0, s[62:63]
	s_mov_b32 m0, s22
	v_lshl_add_u64 v[164:165], v[164:165], 0, s[64:65]
	global_load_lds_dwordx4 v[204:205], off
	s_mov_b32 m0, s23
	s_nop 0
	global_load_lds_dwordx4 v[164:165], off
	s_waitcnt vmcnt(8)
	s_waitcnt lgkmcnt(0)
	s_barrier
	s_setprio 1
	s_waitcnt lgkmcnt(0)
	v_mfma_f32_16x16x32_bf16 v[62:65], v[172:175], v[210:213], v[62:65]
	v_mfma_f32_16x16x32_bf16 v[58:61], v[180:183], v[210:213], v[58:61]
	v_mfma_f32_16x16x32_bf16 v[46:49], v[172:175], v[218:221], v[46:49]
	v_mfma_f32_16x16x32_bf16 v[42:45], v[180:183], v[218:221], v[42:45]
	v_mfma_f32_16x16x32_bf16 v[30:33], v[172:175], v[226:229], v[30:33]
	v_mfma_f32_16x16x32_bf16 v[26:29], v[180:183], v[226:229], v[26:29]
	v_mfma_f32_16x16x32_bf16 v[14:17], v[172:175], v[234:237], v[14:17]
	v_mfma_f32_16x16x32_bf16 v[10:13], v[180:183], v[234:237], v[10:13]
	v_mfma_f32_16x16x32_bf16 v[62:65], v[176:179], v[214:217], v[62:65]
	v_mfma_f32_16x16x32_bf16 v[58:61], v[184:187], v[214:217], v[58:61]
	v_mfma_f32_16x16x32_bf16 v[46:49], v[176:179], v[222:225], v[46:49]
	v_mfma_f32_16x16x32_bf16 v[42:45], v[184:187], v[222:225], v[42:45]
	v_mfma_f32_16x16x32_bf16 v[30:33], v[176:179], v[230:233], v[30:33]
	v_mfma_f32_16x16x32_bf16 v[26:29], v[184:187], v[230:233], v[26:29]
	v_mfma_f32_16x16x32_bf16 v[14:17], v[176:179], v[250:253], v[14:17]
	v_mfma_f32_16x16x32_bf16 v[10:13], v[184:187], v[250:253], v[10:13]
	s_setprio 0
	s_setprio 1
	v_mfma_f32_16x16x32_bf16 v[54:57], v[188:191], v[210:213], v[54:57]
	v_mfma_f32_16x16x32_bf16 v[50:53], v[196:199], v[210:213], v[50:53]
	v_mfma_f32_16x16x32_bf16 v[38:41], v[188:191], v[218:221], v[38:41]
	v_mfma_f32_16x16x32_bf16 v[34:37], v[196:199], v[218:221], v[34:37]
	v_mfma_f32_16x16x32_bf16 v[22:25], v[188:191], v[226:229], v[22:25]
	v_mfma_f32_16x16x32_bf16 v[18:21], v[196:199], v[226:229], v[18:21]
	v_mfma_f32_16x16x32_bf16 v[2:5], v[188:191], v[234:237], v[2:5]
	v_mfma_f32_16x16x32_bf16 v[6:9], v[196:199], v[234:237], v[6:9]
	v_mfma_f32_16x16x32_bf16 v[54:57], v[192:195], v[214:217], v[54:57]
	v_mfma_f32_16x16x32_bf16 v[50:53], v[200:203], v[214:217], v[50:53]
	v_mfma_f32_16x16x32_bf16 v[38:41], v[192:195], v[222:225], v[38:41]
	v_mfma_f32_16x16x32_bf16 v[34:37], v[200:203], v[222:225], v[34:37]
	v_mfma_f32_16x16x32_bf16 v[22:25], v[192:195], v[230:233], v[22:25]
	v_mfma_f32_16x16x32_bf16 v[18:21], v[200:203], v[230:233], v[18:21]
	v_mfma_f32_16x16x32_bf16 v[2:5], v[192:195], v[250:253], v[2:5]
	v_mfma_f32_16x16x32_bf16 v[6:9], v[200:203], v[250:253], v[6:9]
	s_setprio 0
	s_barrier
	s_add_i32 s9, s9, 2
	v_lshl_add_u64 v[150:151], v[150:151], 0, s[72:73]
	s_cmp_gt_u32 s9, 29
	v_lshl_add_u64 v[148:149], v[148:149], 0, s[72:73]
	s_branch .LBB0_1165
.LBB0_1164:
	s_add_i32 s10, 0, 0x10000
	v_add_u32_e32 v154, s10, v163
	s_add_i32 s12, 0, 0x14000
	ds_read_b128 v[172:175], v154
	ds_read_b128 v[176:179], v154 offset:1024
	ds_read_b128 v[180:183], v154 offset:2048
	ds_read_b128 v[184:187], v154 offset:3072
	v_add_u32_e32 v154, s12, v163
	ds_read_b128 v[188:191], v154
	ds_read_b128 v[192:195], v154 offset:1024
	ds_read_b128 v[196:199], v154 offset:2048
	ds_read_b128 v[200:203], v154 offset:3072
	v_lshl_add_u64 v[164:165], v[150:151], 0, s[74:75]
	v_cndmask_b32_e32 v165, v165, v153, vcc
	v_cndmask_b32_e32 v164, v164, v0, vcc
	v_cndmask_b32_e32 v205, v149, v155, vcc
	v_cndmask_b32_e32 v204, v148, v152, vcc
	v_lshl_add_u64 v[206:207], v[150:151], 0, v[142:143]
	s_add_i32 m0, s18, 0xc000
	ds_read_b128 v[210:213], v169
	ds_read_b128 v[214:217], v169 offset:1024
	ds_read_b128 v[218:221], v169 offset:2048
	ds_read_b128 v[222:225], v169 offset:3072
	ds_read_b128 v[226:229], v169 offset:4096
	ds_read_b128 v[230:233], v169 offset:5120
	ds_read_b128 v[234:237], v169 offset:6144
	ds_read_b128 v[250:253], v169 offset:7168
	global_load_lds_dwordx4 v[206:207], off
	v_lshl_add_u64 v[206:207], v[206:207], 0, s[52:53]
	s_add_i32 m0, s18, 0xe000
	s_nop 0
	global_load_lds_dwordx4 v[206:207], off
	s_waitcnt vmcnt(8)
	s_waitcnt lgkmcnt(0)
	s_barrier
	s_setprio 1
	s_waitcnt lgkmcnt(0)
	v_mfma_f32_16x16x32_bf16 v[126:129], v[172:175], v[210:213], v[126:129]
	v_mfma_f32_16x16x32_bf16 v[122:125], v[180:183], v[210:213], v[122:125]
	v_mfma_f32_16x16x32_bf16 v[110:113], v[172:175], v[218:221], v[110:113]
	v_mfma_f32_16x16x32_bf16 v[106:109], v[180:183], v[218:221], v[106:109]
	v_mfma_f32_16x16x32_bf16 v[94:97], v[172:175], v[226:229], v[94:97]
	v_mfma_f32_16x16x32_bf16 v[90:93], v[180:183], v[226:229], v[90:93]
	v_mfma_f32_16x16x32_bf16 v[78:81], v[172:175], v[234:237], v[78:81]
	v_mfma_f32_16x16x32_bf16 v[74:77], v[180:183], v[234:237], v[74:77]
	v_mfma_f32_16x16x32_bf16 v[126:129], v[176:179], v[214:217], v[126:129]
	v_mfma_f32_16x16x32_bf16 v[122:125], v[184:187], v[214:217], v[122:125]
	v_mfma_f32_16x16x32_bf16 v[110:113], v[176:179], v[222:225], v[110:113]
	v_mfma_f32_16x16x32_bf16 v[106:109], v[184:187], v[222:225], v[106:109]
	v_mfma_f32_16x16x32_bf16 v[94:97], v[176:179], v[230:233], v[94:97]
	v_mfma_f32_16x16x32_bf16 v[90:93], v[184:187], v[230:233], v[90:93]
	v_mfma_f32_16x16x32_bf16 v[78:81], v[176:179], v[250:253], v[78:81]
	v_mfma_f32_16x16x32_bf16 v[74:77], v[184:187], v[250:253], v[74:77]
	s_setprio 0
	s_setprio 1
	v_mfma_f32_16x16x32_bf16 v[118:121], v[188:191], v[210:213], v[118:121]
	v_mfma_f32_16x16x32_bf16 v[114:117], v[196:199], v[210:213], v[114:117]
	v_mfma_f32_16x16x32_bf16 v[102:105], v[188:191], v[218:221], v[102:105]
	v_mfma_f32_16x16x32_bf16 v[98:101], v[196:199], v[218:221], v[98:101]
	v_mfma_f32_16x16x32_bf16 v[86:89], v[188:191], v[226:229], v[86:89]
	v_mfma_f32_16x16x32_bf16 v[82:85], v[196:199], v[226:229], v[82:85]
	v_mfma_f32_16x16x32_bf16 v[70:73], v[188:191], v[234:237], v[70:73]
	v_mfma_f32_16x16x32_bf16 v[66:69], v[196:199], v[234:237], v[66:69]
	v_mfma_f32_16x16x32_bf16 v[118:121], v[192:195], v[214:217], v[118:121]
	v_mfma_f32_16x16x32_bf16 v[114:117], v[200:203], v[214:217], v[114:117]
	v_mfma_f32_16x16x32_bf16 v[102:105], v[192:195], v[222:225], v[102:105]
	v_mfma_f32_16x16x32_bf16 v[98:101], v[200:203], v[222:225], v[98:101]
	v_mfma_f32_16x16x32_bf16 v[86:89], v[192:195], v[230:233], v[86:89]
	v_mfma_f32_16x16x32_bf16 v[82:85], v[200:203], v[230:233], v[82:85]
	v_mfma_f32_16x16x32_bf16 v[70:73], v[192:195], v[250:253], v[70:73]
	v_mfma_f32_16x16x32_bf16 v[66:69], v[200:203], v[250:253], v[66:69]
	s_setprio 0
	s_barrier
	s_add_i32 s10, s10, s16
	v_lshl_add_u64 v[204:205], v[204:205], 0, v[134:135]
	s_mov_b32 m0, s10
	ds_read_b128 v[210:213], v169 offset:16384
	ds_read_b128 v[214:217], v169 offset:17408
	ds_read_b128 v[218:221], v169 offset:18432
	ds_read_b128 v[222:225], v169 offset:19456
	ds_read_b128 v[226:229], v169 offset:20480
	ds_read_b128 v[230:233], v169 offset:21504
	ds_read_b128 v[234:237], v169 offset:22528
	ds_read_b128 v[250:253], v169 offset:23552
	global_load_lds_dwordx4 v[204:205], off
	v_lshl_add_u64 v[206:207], v[204:205], 0, s[54:55]
	s_add_i32 m0, s10, 0x2000
	s_add_i32 s10, s12, s16
	global_load_lds_dwordx4 v[206:207], off
	v_lshl_add_u64 v[206:207], v[204:205], 0, s[100:101]
	s_mov_b32 m0, s10
	v_lshl_add_u64 v[164:165], v[164:165], 0, v[136:137]
	global_load_lds_dwordx4 v[206:207], off
	v_lshl_add_u64 v[206:207], v[206:207], 0, s[54:55]
	s_add_i32 m0, s10, 0x2000
	s_nop 0
	global_load_lds_dwordx4 v[206:207], off
	s_mov_b32 m0, s18
	v_lshl_add_u64 v[206:207], v[164:165], 0, s[52:53]
	global_load_lds_dwordx4 v[164:165], off
	s_mov_b32 m0, s19
	s_nop 0
	global_load_lds_dwordx4 v[206:207], off
	s_waitcnt vmcnt(8)
	s_waitcnt lgkmcnt(0)
	s_barrier
	s_setprio 1
	s_waitcnt lgkmcnt(0)
	v_mfma_f32_16x16x32_bf16 v[62:65], v[172:175], v[210:213], v[62:65]
	v_mfma_f32_16x16x32_bf16 v[58:61], v[180:183], v[210:213], v[58:61]
	v_mfma_f32_16x16x32_bf16 v[46:49], v[172:175], v[218:221], v[46:49]
	v_mfma_f32_16x16x32_bf16 v[42:45], v[180:183], v[218:221], v[42:45]
	v_mfma_f32_16x16x32_bf16 v[30:33], v[172:175], v[226:229], v[30:33]
	v_mfma_f32_16x16x32_bf16 v[26:29], v[180:183], v[226:229], v[26:29]
	v_mfma_f32_16x16x32_bf16 v[14:17], v[172:175], v[234:237], v[14:17]
	v_mfma_f32_16x16x32_bf16 v[10:13], v[180:183], v[234:237], v[10:13]
	v_mfma_f32_16x16x32_bf16 v[62:65], v[176:179], v[214:217], v[62:65]
	v_mfma_f32_16x16x32_bf16 v[58:61], v[184:187], v[214:217], v[58:61]
	v_mfma_f32_16x16x32_bf16 v[46:49], v[176:179], v[222:225], v[46:49]
	v_mfma_f32_16x16x32_bf16 v[42:45], v[184:187], v[222:225], v[42:45]
	v_mfma_f32_16x16x32_bf16 v[30:33], v[176:179], v[230:233], v[30:33]
	v_mfma_f32_16x16x32_bf16 v[26:29], v[184:187], v[230:233], v[26:29]
	v_mfma_f32_16x16x32_bf16 v[14:17], v[176:179], v[250:253], v[14:17]
	v_mfma_f32_16x16x32_bf16 v[10:13], v[184:187], v[250:253], v[10:13]
	s_setprio 0
	s_setprio 1
	v_mfma_f32_16x16x32_bf16 v[54:57], v[188:191], v[210:213], v[54:57]
	v_mfma_f32_16x16x32_bf16 v[50:53], v[196:199], v[210:213], v[50:53]
	v_mfma_f32_16x16x32_bf16 v[38:41], v[188:191], v[218:221], v[38:41]
	v_mfma_f32_16x16x32_bf16 v[34:37], v[196:199], v[218:221], v[34:37]
	v_mfma_f32_16x16x32_bf16 v[22:25], v[188:191], v[226:229], v[22:25]
	v_mfma_f32_16x16x32_bf16 v[18:21], v[196:199], v[226:229], v[18:21]
	v_mfma_f32_16x16x32_bf16 v[2:5], v[188:191], v[234:237], v[2:5]
	v_mfma_f32_16x16x32_bf16 v[6:9], v[196:199], v[234:237], v[6:9]
	v_mfma_f32_16x16x32_bf16 v[54:57], v[192:195], v[214:217], v[54:57]
	v_mfma_f32_16x16x32_bf16 v[50:53], v[200:203], v[214:217], v[50:53]
	v_mfma_f32_16x16x32_bf16 v[38:41], v[192:195], v[222:225], v[38:41]
	v_mfma_f32_16x16x32_bf16 v[34:37], v[200:203], v[222:225], v[34:37]
	v_mfma_f32_16x16x32_bf16 v[22:25], v[192:195], v[230:233], v[22:25]
	v_mfma_f32_16x16x32_bf16 v[18:21], v[200:203], v[230:233], v[18:21]
	v_mfma_f32_16x16x32_bf16 v[2:5], v[192:195], v[250:253], v[2:5]
	v_mfma_f32_16x16x32_bf16 v[6:9], v[200:203], v[250:253], v[6:9]
	s_setprio 0
	s_barrier
	s_add_i32 s10, 0, 0x18000
	v_add_u32_e32 v154, s10, v163
	s_add_i32 s12, 0, 0x1c000
	ds_read_b128 v[172:175], v154
	ds_read_b128 v[176:179], v154 offset:1024
	ds_read_b128 v[180:183], v154 offset:2048
	ds_read_b128 v[184:187], v154 offset:3072
	v_add_u32_e32 v154, s12, v163
	ds_read_b128 v[188:191], v154
	ds_read_b128 v[192:195], v154 offset:1024
	ds_read_b128 v[196:199], v154 offset:2048
	ds_read_b128 v[200:203], v154 offset:3072
	s_mov_b32 m0, s20
	v_lshl_add_u64 v[206:207], v[164:165], 0, s[54:55]
	ds_read_b128 v[210:213], v169 offset:32768
	ds_read_b128 v[214:217], v169 offset:33792
	ds_read_b128 v[218:221], v169 offset:34816
	ds_read_b128 v[222:225], v169 offset:35840
	ds_read_b128 v[226:229], v169 offset:36864
	ds_read_b128 v[230:233], v169 offset:37888
	ds_read_b128 v[234:237], v169 offset:38912
	ds_read_b128 v[250:253], v169 offset:39936
	global_load_lds_dwordx4 v[206:207], off
	v_lshl_add_u64 v[206:207], v[164:165], 0, s[56:57]
	s_mov_b32 m0, s21
	s_nop 0
	global_load_lds_dwordx4 v[206:207], off
	s_waitcnt vmcnt(8)
	s_waitcnt lgkmcnt(0)
	s_barrier
	s_setprio 1
	s_waitcnt lgkmcnt(0)
	v_mfma_f32_16x16x32_bf16 v[126:129], v[172:175], v[210:213], v[126:129]
	v_mfma_f32_16x16x32_bf16 v[122:125], v[180:183], v[210:213], v[122:125]
	v_mfma_f32_16x16x32_bf16 v[110:113], v[172:175], v[218:221], v[110:113]
	v_mfma_f32_16x16x32_bf16 v[106:109], v[180:183], v[218:221], v[106:109]
	v_mfma_f32_16x16x32_bf16 v[94:97], v[172:175], v[226:229], v[94:97]
	v_mfma_f32_16x16x32_bf16 v[90:93], v[180:183], v[226:229], v[90:93]
	v_mfma_f32_16x16x32_bf16 v[78:81], v[172:175], v[234:237], v[78:81]
	v_mfma_f32_16x16x32_bf16 v[74:77], v[180:183], v[234:237], v[74:77]
	v_mfma_f32_16x16x32_bf16 v[126:129], v[176:179], v[214:217], v[126:129]
	v_mfma_f32_16x16x32_bf16 v[122:125], v[184:187], v[214:217], v[122:125]
	v_mfma_f32_16x16x32_bf16 v[110:113], v[176:179], v[222:225], v[110:113]
	v_mfma_f32_16x16x32_bf16 v[106:109], v[184:187], v[222:225], v[106:109]
	v_mfma_f32_16x16x32_bf16 v[94:97], v[176:179], v[230:233], v[94:97]
	v_mfma_f32_16x16x32_bf16 v[90:93], v[184:187], v[230:233], v[90:93]
	v_mfma_f32_16x16x32_bf16 v[78:81], v[176:179], v[250:253], v[78:81]
	v_mfma_f32_16x16x32_bf16 v[74:77], v[184:187], v[250:253], v[74:77]
	s_setprio 0
	s_setprio 1
	v_mfma_f32_16x16x32_bf16 v[118:121], v[188:191], v[210:213], v[118:121]
	v_mfma_f32_16x16x32_bf16 v[114:117], v[196:199], v[210:213], v[114:117]
	v_mfma_f32_16x16x32_bf16 v[102:105], v[188:191], v[218:221], v[102:105]
	v_mfma_f32_16x16x32_bf16 v[98:101], v[196:199], v[218:221], v[98:101]
	v_mfma_f32_16x16x32_bf16 v[86:89], v[188:191], v[226:229], v[86:89]
	v_mfma_f32_16x16x32_bf16 v[82:85], v[196:199], v[226:229], v[82:85]
	v_mfma_f32_16x16x32_bf16 v[70:73], v[188:191], v[234:237], v[70:73]
	v_mfma_f32_16x16x32_bf16 v[66:69], v[196:199], v[234:237], v[66:69]
	v_mfma_f32_16x16x32_bf16 v[118:121], v[192:195], v[214:217], v[118:121]
	v_mfma_f32_16x16x32_bf16 v[114:117], v[200:203], v[214:217], v[114:117]
	v_mfma_f32_16x16x32_bf16 v[102:105], v[192:195], v[222:225], v[102:105]
	v_mfma_f32_16x16x32_bf16 v[98:101], v[200:203], v[222:225], v[98:101]
	v_mfma_f32_16x16x32_bf16 v[86:89], v[192:195], v[230:233], v[86:89]
	v_mfma_f32_16x16x32_bf16 v[82:85], v[200:203], v[230:233], v[82:85]
	v_mfma_f32_16x16x32_bf16 v[70:73], v[192:195], v[250:253], v[70:73]
	v_mfma_f32_16x16x32_bf16 v[66:69], v[200:203], v[250:253], v[66:69]
	s_setprio 0
	s_barrier
	s_add_i32 s10, s10, s16
	v_lshl_add_u64 v[206:207], v[204:205], 0, s[62:63]
	s_mov_b32 m0, s10
	ds_read_b128 v[210:213], v169 offset:49152
	ds_read_b128 v[214:217], v169 offset:50176
	ds_read_b128 v[218:221], v169 offset:51200
	ds_read_b128 v[222:225], v169 offset:52224
	ds_read_b128 v[226:229], v169 offset:53248
	ds_read_b128 v[230:233], v169 offset:54272
	ds_read_b128 v[234:237], v169 offset:55296
	ds_read_b128 v[250:253], v169 offset:56320
	global_load_lds_dwordx4 v[206:207], off
	v_lshl_add_u64 v[206:207], v[204:205], 0, s[66:67]
	s_add_i32 m0, s10, 0x2000
	s_add_i32 s10, s12, s16
	global_load_lds_dwordx4 v[206:207], off
	v_lshl_add_u64 v[206:207], v[204:205], 0, s[62:63]
	v_lshl_add_u64 v[206:207], v[206:207], 0, s[100:101]
	s_mov_b32 m0, s10
	v_lshl_add_u64 v[204:205], v[206:207], 0, s[54:55]
	global_load_lds_dwordx4 v[206:207], off
	s_add_i32 m0, s10, 0x2000
	s_nop 0
	global_load_lds_dwordx4 v[204:205], off
	v_lshl_add_u64 v[204:205], v[164:165], 0, s[62:63]
	s_mov_b32 m0, s22
	v_lshl_add_u64 v[164:165], v[164:165], 0, s[64:65]
	global_load_lds_dwordx4 v[204:205], off
	s_mov_b32 m0, s23
	s_nop 0
	global_load_lds_dwordx4 v[164:165], off
	s_waitcnt vmcnt(8)
	s_waitcnt lgkmcnt(0)
	s_barrier
	s_setprio 1
	s_waitcnt lgkmcnt(0)
	v_mfma_f32_16x16x32_bf16 v[62:65], v[172:175], v[210:213], v[62:65]
	v_mfma_f32_16x16x32_bf16 v[58:61], v[180:183], v[210:213], v[58:61]
	v_mfma_f32_16x16x32_bf16 v[46:49], v[172:175], v[218:221], v[46:49]
	v_mfma_f32_16x16x32_bf16 v[42:45], v[180:183], v[218:221], v[42:45]
	v_mfma_f32_16x16x32_bf16 v[30:33], v[172:175], v[226:229], v[30:33]
	v_mfma_f32_16x16x32_bf16 v[26:29], v[180:183], v[226:229], v[26:29]
	v_mfma_f32_16x16x32_bf16 v[14:17], v[172:175], v[234:237], v[14:17]
	v_mfma_f32_16x16x32_bf16 v[10:13], v[180:183], v[234:237], v[10:13]
	v_mfma_f32_16x16x32_bf16 v[62:65], v[176:179], v[214:217], v[62:65]
	v_mfma_f32_16x16x32_bf16 v[58:61], v[184:187], v[214:217], v[58:61]
	v_mfma_f32_16x16x32_bf16 v[46:49], v[176:179], v[222:225], v[46:49]
	v_mfma_f32_16x16x32_bf16 v[42:45], v[184:187], v[222:225], v[42:45]
	v_mfma_f32_16x16x32_bf16 v[30:33], v[176:179], v[230:233], v[30:33]
	v_mfma_f32_16x16x32_bf16 v[26:29], v[184:187], v[230:233], v[26:29]
	v_mfma_f32_16x16x32_bf16 v[14:17], v[176:179], v[250:253], v[14:17]
	v_mfma_f32_16x16x32_bf16 v[10:13], v[184:187], v[250:253], v[10:13]
	s_setprio 0
	s_setprio 1
	v_mfma_f32_16x16x32_bf16 v[54:57], v[188:191], v[210:213], v[54:57]
	v_mfma_f32_16x16x32_bf16 v[50:53], v[196:199], v[210:213], v[50:53]
	v_mfma_f32_16x16x32_bf16 v[38:41], v[188:191], v[218:221], v[38:41]
	v_mfma_f32_16x16x32_bf16 v[34:37], v[196:199], v[218:221], v[34:37]
	v_mfma_f32_16x16x32_bf16 v[22:25], v[188:191], v[226:229], v[22:25]
	v_mfma_f32_16x16x32_bf16 v[18:21], v[196:199], v[226:229], v[18:21]
	v_mfma_f32_16x16x32_bf16 v[2:5], v[188:191], v[234:237], v[2:5]
	v_mfma_f32_16x16x32_bf16 v[6:9], v[196:199], v[234:237], v[6:9]
	v_mfma_f32_16x16x32_bf16 v[54:57], v[192:195], v[214:217], v[54:57]
	v_mfma_f32_16x16x32_bf16 v[50:53], v[200:203], v[214:217], v[50:53]
	v_mfma_f32_16x16x32_bf16 v[38:41], v[192:195], v[222:225], v[38:41]
	v_mfma_f32_16x16x32_bf16 v[34:37], v[200:203], v[222:225], v[34:37]
	v_mfma_f32_16x16x32_bf16 v[22:25], v[192:195], v[230:233], v[22:25]
	v_mfma_f32_16x16x32_bf16 v[18:21], v[200:203], v[230:233], v[18:21]
	v_mfma_f32_16x16x32_bf16 v[2:5], v[192:195], v[250:253], v[2:5]
	v_mfma_f32_16x16x32_bf16 v[6:9], v[200:203], v[250:253], v[6:9]
	s_setprio 0
	s_barrier
	s_add_i32 s9, s9, 2
	v_lshl_add_u64 v[150:151], v[150:151], 0, s[72:73]
	s_cmp_gt_u32 s9, 29
	v_lshl_add_u64 v[148:149], v[148:149], 0, s[72:73]
	s_cbranch_scc1 .LBB0_1167

.LBB0_1167:
.LBB0_1169:
	ds_read_b128 v[150:153], v170
	ds_read_b128 v[154:157], v170 offset:2048
	v_add_u32_e32 v148, s7, v161
	v_and_b32_e32 v171, 8, v161
	v_sub_u32_e32 v148, v148, v171
	v_lshl_or_b32 v164, s11, 8, v168
	v_ashrrev_i32_e32 v165, 31, v164
	s_waitcnt lgkmcnt(0)
	v_lshlrev_b32_e32 v0, 16, v150
	v_and_b32_e32 v149, 0xffff0000, v150
	v_add_f32_e32 v0, v0, v149
	v_lshlrev_b32_e32 v149, 16, v151
	v_and_b32_e32 v150, 0xffff0000, v151
	v_add_f32_e32 v149, v149, v150
	v_add_f32_e32 v0, v0, v149
	v_lshlrev_b32_e32 v149, 16, v152
	v_and_b32_e32 v150, 0xffff0000, v152
	v_add_f32_e32 v149, v149, v150
	v_lshlrev_b32_e32 v150, 16, v153
	v_and_b32_e32 v151, 0xffff0000, v153
	v_add_f32_e32 v150, v150, v151
	v_add_f32_e32 v149, v149, v150
	v_add_f32_e32 v0, v0, v149
	v_mov_b32_e32 v149, v0
	ds_read_b128 v[150:153], v170 offset:1024
	ds_read_b128 v[172:175], v170 offset:8192
	v_permlane16_swap_b32_e32 v0, v149
	v_add_f32_e32 v0, v0, v149
	v_mov_b32_e32 v149, v0
	s_nop 1
	v_permlane32_swap_b32_e32 v0, v149
	v_add_f32_e32 v0, v0, v149
	s_waitcnt lgkmcnt(0)
	v_lshlrev_b32_e32 v149, 16, v150
	v_and_b32_e32 v150, 0xffff0000, v150
	v_add_f32_e32 v149, v149, v150
	v_lshlrev_b32_e32 v150, 16, v151
	v_and_b32_e32 v151, 0xffff0000, v151
	v_add_f32_e32 v150, v150, v151
	v_add_f32_e32 v149, v149, v150
	v_lshlrev_b32_e32 v150, 16, v152
	v_and_b32_e32 v151, 0xffff0000, v152
	v_add_f32_e32 v150, v150, v151
	v_lshlrev_b32_e32 v151, 16, v153
	v_and_b32_e32 v152, 0xffff0000, v153
	v_add_f32_e32 v151, v151, v152
	v_add_f32_e32 v150, v150, v151
	v_add_f32_e32 v149, v149, v150
	v_mov_b32_e32 v150, v149
	s_nop 1
	v_permlane16_swap_b32_e32 v149, v150
	v_add_f32_e32 v149, v149, v150
	v_mov_b32_e32 v150, v149
	s_nop 1
	v_permlane32_swap_b32_e32 v149, v150
	v_add_f32_e32 v149, v149, v150
	v_fmamk_f32 v149, v149, 0x3a000000, v240
	v_rsq_f32_e32 v152, v149
	v_lshlrev_b32_e32 v149, 16, v154
	v_and_b32_e32 v150, 0xffff0000, v154
	v_add_f32_e32 v149, v149, v150
	v_lshlrev_b32_e32 v150, 16, v155
	v_and_b32_e32 v151, 0xffff0000, v155
	v_add_f32_e32 v150, v150, v151
	v_add_f32_e32 v149, v149, v150
	v_lshlrev_b32_e32 v150, 16, v156
	v_and_b32_e32 v151, 0xffff0000, v156
	v_add_f32_e32 v150, v150, v151
	v_lshlrev_b32_e32 v151, 16, v157
	v_and_b32_e32 v153, 0xffff0000, v157
	v_add_f32_e32 v151, v151, v153
	v_add_f32_e32 v150, v150, v151
	v_add_f32_e32 v149, v149, v150
	v_mov_b32_e32 v150, v149
	s_nop 1
	v_permlane16_swap_b32_e32 v149, v150
	v_add_f32_e32 v149, v149, v150
	ds_read_b128 v[154:157], v170 offset:3072
	v_mov_b32_e32 v150, v149
	s_nop 1
	v_permlane32_swap_b32_e32 v149, v150
	v_add_f32_e32 v149, v149, v150
	v_fmamk_f32 v149, v149, 0x3a000000, v240
	v_rsq_f32_e32 v150, v149
	s_waitcnt lgkmcnt(0)
	v_lshlrev_b32_e32 v149, 16, v154
	v_and_b32_e32 v151, 0xffff0000, v154
	v_add_f32_e32 v149, v149, v151
	v_lshlrev_b32_e32 v151, 16, v155
	v_and_b32_e32 v153, 0xffff0000, v155
	v_add_f32_e32 v151, v151, v153
	v_add_f32_e32 v149, v149, v151
	v_lshlrev_b32_e32 v151, 16, v156
	v_and_b32_e32 v153, 0xffff0000, v156
	v_add_f32_e32 v151, v151, v153
	v_lshlrev_b32_e32 v153, 16, v157
	v_and_b32_e32 v154, 0xffff0000, v157
	v_add_f32_e32 v153, v153, v154
	v_add_f32_e32 v151, v151, v153
	v_add_f32_e32 v149, v149, v151
	v_mov_b32_e32 v151, v149
	s_nop 1
	v_permlane16_swap_b32_e32 v149, v151
	v_add_f32_e32 v149, v149, v151
	v_mov_b32_e32 v151, v149
	s_nop 1
	v_permlane32_swap_b32_e32 v149, v151
	v_add_f32_e32 v149, v149, v151
	v_fmamk_f32 v149, v149, 0x3a000000, v240
	v_rsq_f32_e32 v156, v149
	v_lshlrev_b32_e32 v149, 16, v172
	v_and_b32_e32 v151, 0xffff0000, v172
	s_mov_b64 vcc, s[2:3]
	s_cbranch_vccz .Lalign_skip_2
	s_barrier
.Lalign_skip_2:
	v_add_f32_e32 v149, v149, v151
	v_lshlrev_b32_e32 v151, 16, v173
	v_and_b32_e32 v153, 0xffff0000, v173
	v_add_f32_e32 v151, v151, v153
	v_add_f32_e32 v149, v149, v151
	v_lshlrev_b32_e32 v151, 16, v174
	v_and_b32_e32 v153, 0xffff0000, v174
	v_add_f32_e32 v151, v151, v153
	v_lshlrev_b32_e32 v153, 16, v175
	v_and_b32_e32 v154, 0xffff0000, v175
	v_add_f32_e32 v153, v153, v154
	v_add_f32_e32 v151, v151, v153
	v_add_f32_e32 v149, v149, v151
	v_mov_b32_e32 v151, v149
	s_nop 1
	v_permlane16_swap_b32_e32 v149, v151
	v_add_f32_e32 v149, v149, v151
	ds_read_b128 v[172:175], v170 offset:9216
	v_mov_b32_e32 v151, v149
	s_nop 1
	v_permlane32_swap_b32_e32 v149, v151
	v_add_f32_e32 v149, v149, v151
	v_fmamk_f32 v149, v149, 0x3a000000, v240
	v_rsq_f32_e32 v154, v149
	s_waitcnt lgkmcnt(0)
	v_lshlrev_b32_e32 v149, 16, v172
	v_and_b32_e32 v151, 0xffff0000, v172
	v_add_f32_e32 v149, v149, v151
	v_lshlrev_b32_e32 v151, 16, v173
	v_and_b32_e32 v153, 0xffff0000, v173
	v_add_f32_e32 v151, v151, v153
	v_add_f32_e32 v149, v149, v151
	v_lshlrev_b32_e32 v151, 16, v174
	v_and_b32_e32 v153, 0xffff0000, v174
	v_add_f32_e32 v151, v151, v153
	v_lshlrev_b32_e32 v153, 16, v175
	v_and_b32_e32 v155, 0xffff0000, v175
	v_add_f32_e32 v153, v153, v155
	v_add_f32_e32 v151, v151, v153
	v_add_f32_e32 v149, v149, v151
	v_mov_b32_e32 v151, v149
	s_nop 1
	v_permlane16_swap_b32_e32 v149, v151
	v_add_f32_e32 v149, v149, v151
	ds_read_b128 v[172:175], v170 offset:10240
	v_mov_b32_e32 v151, v149
	s_nop 1
	v_permlane32_swap_b32_e32 v149, v151
	v_add_f32_e32 v149, v149, v151
	v_fmamk_f32 v149, v149, 0x3a000000, v240
	v_rsq_f32_e32 v160, v149
	s_waitcnt lgkmcnt(0)
	v_lshlrev_b32_e32 v149, 16, v172
	v_and_b32_e32 v151, 0xffff0000, v172
	v_add_f32_e32 v149, v149, v151
	v_lshlrev_b32_e32 v151, 16, v173
	v_and_b32_e32 v153, 0xffff0000, v173
	v_add_f32_e32 v151, v151, v153
	v_add_f32_e32 v149, v149, v151
	v_lshlrev_b32_e32 v151, 16, v174
	v_and_b32_e32 v153, 0xffff0000, v174
	v_add_f32_e32 v151, v151, v153
	v_lshlrev_b32_e32 v153, 16, v175
	v_and_b32_e32 v155, 0xffff0000, v175
	v_add_f32_e32 v153, v153, v155
	v_add_f32_e32 v151, v151, v153
	v_add_f32_e32 v149, v149, v151
	v_mov_b32_e32 v151, v149
	s_nop 1
	v_permlane16_swap_b32_e32 v149, v151
	v_add_f32_e32 v149, v149, v151
	ds_read_b128 v[172:175], v170 offset:11264
	v_mov_b32_e32 v151, v149
	s_nop 1
	v_permlane32_swap_b32_e32 v149, v151
	v_add_f32_e32 v149, v149, v151
	v_fmamk_f32 v149, v149, 0x3a000000, v240
	v_rsq_f32_e32 v158, v149
	s_waitcnt lgkmcnt(0)
	v_lshlrev_b32_e32 v149, 16, v172
	v_and_b32_e32 v151, 0xffff0000, v172
	v_add_f32_e32 v149, v149, v151
	v_lshlrev_b32_e32 v151, 16, v173
	v_and_b32_e32 v153, 0xffff0000, v173
	v_add_f32_e32 v151, v151, v153
	v_add_f32_e32 v149, v149, v151
	v_lshlrev_b32_e32 v151, 16, v174
	v_and_b32_e32 v153, 0xffff0000, v174
	v_add_f32_e32 v151, v151, v153
	v_lshlrev_b32_e32 v153, 16, v175
	v_and_b32_e32 v155, 0xffff0000, v175
	v_add_f32_e32 v153, v153, v155
	v_add_f32_e32 v151, v151, v153
	v_add_f32_e32 v149, v149, v151
	v_mov_b32_e32 v151, v149
	v_fmamk_f32 v0, v0, 0x3a000000, v240
	s_nop 0
	v_permlane16_swap_b32_e32 v149, v151
	v_rsq_f32_e32 v0, v0
	v_add_f32_e32 v149, v149, v151
	v_mov_b32_e32 v151, v149
	s_nop 1
	v_permlane32_swap_b32_e32 v149, v151
	v_add_f32_e32 v149, v149, v151
	v_fmamk_f32 v149, v149, 0x3a000000, v240
	v_pk_mul_f32 v[122:123], v[122:123], v[0:1] op_sel_hi:[1,0]
	v_rsq_f32_e32 v162, v149
	v_ashrrev_i32_e32 v149, 31, v148
	v_max_f32_e32 v122, 0, v122
	v_lshl_add_u64 v[172:173], v[164:165], 1, v[138:139]
	v_lshlrev_b64 v[164:165], 14, v[148:149]
	v_pk_mul_f32 v[124:125], v[124:125], v[0:1] op_sel_hi:[1,0]
	v_mul_f32_e32 v149, v122, v122
	v_max_f32_e32 v122, 0, v123
	v_pk_mul_f32 v[126:127], v[126:127], v[0:1] op_sel_hi:[1,0]
	v_mul_f32_e32 v151, v122, v122
	v_max_f32_e32 v122, 0, v124
	v_pk_mul_f32 v[114:115], v[114:115], v[0:1] op_sel_hi:[1,0]
	v_pk_mul_f32 v[128:129], v[128:129], v[0:1] op_sel_hi:[1,0]
	v_max_f32_e32 v126, 0, v126
	v_max_f32_e32 v127, 0, v127
	v_mul_f32_e32 v153, v122, v122
	v_max_f32_e32 v122, 0, v125
	v_pk_mul_f32 v[120:121], v[120:121], v[0:1] op_sel_hi:[1,0]
	v_pk_mul_f32 v[118:119], v[118:119], v[0:1] op_sel_hi:[1,0]
	v_max_f32_e32 v114, 0, v114
	v_lshl_add_u64 v[164:165], v[172:173], 0, v[164:165]
	v_mul_f32_e32 v126, v126, v126
	v_mul_f32_e32 v127, v127, v127
	v_max_f32_e32 v128, 0, v128
	v_max_f32_e32 v129, 0, v129
	v_mul_f32_e32 v125, v122, v122
	v_cvt_pk_bf16_f32 v122, v126, v127
	v_pk_mul_f32 v[116:117], v[116:117], v[0:1] op_sel_hi:[1,0]
	v_max_f32_e32 v0, 0, v118
	v_max_f32_e32 v118, 0, v119
	v_max_f32_e32 v119, 0, v120
	v_max_f32_e32 v120, 0, v121
	v_mul_f32_e32 v121, v114, v114
	v_max_f32_e32 v114, 0, v115
	v_mul_f32_e32 v128, v128, v128
	v_mul_f32_e32 v129, v129, v129
	v_cvt_pk_bf16_f32 v123, v128, v129
	v_cvt_pk_bf16_f32 v124, v149, v151
	v_cvt_pk_bf16_f32 v125, v153, v125
	v_pk_mul_f32 v[106:107], v[106:107], v[152:153] op_sel_hi:[1,0]
	v_mul_f32_e32 v0, v0, v0
	v_mul_f32_e32 v238, v114, v114
	v_max_f32_e32 v114, 0, v116
	v_mul_f32_e32 v239, v114, v114
	v_max_f32_e32 v114, 0, v117
	v_mul_f32_e32 v118, v118, v118
	v_mul_f32_e32 v117, v114, v114
	v_cvt_pk_bf16_f32 v114, v0, v118
	v_pk_mul_f32 v[112:113], v[112:113], v[152:153] op_sel_hi:[1,0]
	v_pk_mul_f32 v[110:111], v[110:111], v[152:153] op_sel_hi:[1,0]
	v_max_f32_e32 v106, 0, v106
	v_mul_f32_e32 v119, v119, v119
	v_mul_f32_e32 v120, v120, v120
	v_cvt_pk_bf16_f32 v115, v119, v120
	v_cvt_pk_bf16_f32 v116, v121, v238
	v_cvt_pk_bf16_f32 v117, v239, v117
	v_mov_b32_e32 v208, v122
	v_mov_b32_e32 v209, v123
	v_mov_b32_e32 v238, v124
	v_mov_b32_e32 v239, v125
	v_mov_b32_dpp v122, v114 row_ror:8 row_mask:0xf bank_mask:0xc
	v_mov_b32_dpp v123, v115 row_ror:8 row_mask:0xf bank_mask:0xc
	v_mov_b32_dpp v124, v116 row_ror:8 row_mask:0xf bank_mask:0xc
	v_mov_b32_dpp v125, v117 row_ror:8 row_mask:0xf bank_mask:0xc
	v_mov_b32_dpp v114, v208 row_ror:8 row_mask:0xf bank_mask:0x3
	v_mov_b32_dpp v115, v209 row_ror:8 row_mask:0xf bank_mask:0x3
	v_mov_b32_dpp v116, v238 row_ror:8 row_mask:0xf bank_mask:0x3
	v_mov_b32_dpp v117, v239 row_ror:8 row_mask:0xf bank_mask:0x3
	global_store_dwordx4 v[164:165], v[122:125], off
	v_lshl_add_u64 v[208:209], v[164:165], 0, s[100:101]
	global_store_dwordx4 v[208:209], v[114:117], off
	v_pk_mul_f32 v[108:109], v[108:109], v[152:153] op_sel_hi:[1,0]
	v_max_f32_e32 v0, 0, v110
	v_or_b32_e32 v114, 16, v148
	v_max_f32_e32 v110, 0, v111
	v_max_f32_e32 v111, 0, v112
	v_max_f32_e32 v112, 0, v113
	v_mul_f32_e32 v113, v106, v106
	v_max_f32_e32 v106, 0, v107
	v_ashrrev_i32_e32 v115, 31, v114
	v_mul_f32_e32 v116, v106, v106
	v_max_f32_e32 v106, 0, v108
	v_pk_mul_f32 v[98:99], v[98:99], v[152:153] op_sel_hi:[1,0]
	v_lshlrev_b64 v[114:115], 14, v[114:115]
	v_mul_f32_e32 v0, v0, v0
	v_mul_f32_e32 v117, v106, v106
	v_max_f32_e32 v106, 0, v109
	v_pk_mul_f32 v[104:105], v[104:105], v[152:153] op_sel_hi:[1,0]
	v_pk_mul_f32 v[102:103], v[102:103], v[152:153] op_sel_hi:[1,0]
	v_max_f32_e32 v98, 0, v98
	v_lshl_add_u64 v[114:115], v[172:173], 0, v[114:115]
	v_mul_f32_e32 v110, v110, v110
	v_mul_f32_e32 v109, v106, v106
	v_cvt_pk_bf16_f32 v106, v0, v110
	v_pk_mul_f32 v[100:101], v[100:101], v[152:153] op_sel_hi:[1,0]
	v_max_f32_e32 v0, 0, v102
	v_max_f32_e32 v102, 0, v103
	v_max_f32_e32 v103, 0, v104
	v_max_f32_e32 v104, 0, v105
	v_mul_f32_e32 v105, v98, v98
	v_max_f32_e32 v98, 0, v99
	v_mul_f32_e32 v111, v111, v111
	v_mul_f32_e32 v112, v112, v112
	v_cvt_pk_bf16_f32 v107, v111, v112
	v_cvt_pk_bf16_f32 v108, v113, v116
	v_cvt_pk_bf16_f32 v109, v117, v109
	v_pk_mul_f32 v[90:91], v[90:91], v[150:151] op_sel_hi:[1,0]
	v_mul_f32_e32 v0, v0, v0
	v_mul_f32_e32 v238, v98, v98
	v_max_f32_e32 v98, 0, v100
	v_mul_f32_e32 v239, v98, v98
	v_max_f32_e32 v98, 0, v101
	v_mul_f32_e32 v102, v102, v102
	v_mul_f32_e32 v101, v98, v98
	v_cvt_pk_bf16_f32 v98, v0, v102
	v_pk_mul_f32 v[96:97], v[96:97], v[150:151] op_sel_hi:[1,0]
	v_pk_mul_f32 v[94:95], v[94:95], v[150:151] op_sel_hi:[1,0]
	v_max_f32_e32 v90, 0, v90
	v_mul_f32_e32 v103, v103, v103
	v_mul_f32_e32 v104, v104, v104
	v_cvt_pk_bf16_f32 v99, v103, v104
	v_cvt_pk_bf16_f32 v100, v105, v238
	v_cvt_pk_bf16_f32 v101, v239, v101
	v_mov_b32_e32 v208, v106
	v_mov_b32_e32 v209, v107
	v_mov_b32_e32 v238, v108
	v_mov_b32_e32 v239, v109
	v_mov_b32_dpp v106, v98 row_ror:8 row_mask:0xf bank_mask:0xc
	v_mov_b32_dpp v107, v99 row_ror:8 row_mask:0xf bank_mask:0xc
	v_mov_b32_dpp v108, v100 row_ror:8 row_mask:0xf bank_mask:0xc
	v_mov_b32_dpp v109, v101 row_ror:8 row_mask:0xf bank_mask:0xc
	v_mov_b32_dpp v98, v208 row_ror:8 row_mask:0xf bank_mask:0x3
	v_mov_b32_dpp v99, v209 row_ror:8 row_mask:0xf bank_mask:0x3
	v_mov_b32_dpp v100, v238 row_ror:8 row_mask:0xf bank_mask:0x3
	v_mov_b32_dpp v101, v239 row_ror:8 row_mask:0xf bank_mask:0x3
	global_store_dwordx4 v[114:115], v[106:109], off
	v_lshl_add_u64 v[208:209], v[114:115], 0, s[100:101]
	global_store_dwordx4 v[208:209], v[98:101], off
	v_pk_mul_f32 v[92:93], v[92:93], v[150:151] op_sel_hi:[1,0]
	v_max_f32_e32 v0, 0, v94
	v_or_b32_e32 v98, 32, v148
	v_max_f32_e32 v94, 0, v95
	v_max_f32_e32 v95, 0, v96
	v_max_f32_e32 v96, 0, v97
	v_mul_f32_e32 v97, v90, v90
	v_max_f32_e32 v90, 0, v91
	v_ashrrev_i32_e32 v99, 31, v98
	v_mul_f32_e32 v100, v90, v90
	v_max_f32_e32 v90, 0, v92
	v_pk_mul_f32 v[82:83], v[82:83], v[150:151] op_sel_hi:[1,0]
	v_lshlrev_b64 v[98:99], 14, v[98:99]
	v_mul_f32_e32 v0, v0, v0
	v_mul_f32_e32 v101, v90, v90
	v_max_f32_e32 v90, 0, v93
	v_pk_mul_f32 v[88:89], v[88:89], v[150:151] op_sel_hi:[1,0]
	v_pk_mul_f32 v[86:87], v[86:87], v[150:151] op_sel_hi:[1,0]
	v_max_f32_e32 v82, 0, v82
	v_lshl_add_u64 v[98:99], v[172:173], 0, v[98:99]
	v_mul_f32_e32 v94, v94, v94
	v_mul_f32_e32 v93, v90, v90
	v_cvt_pk_bf16_f32 v90, v0, v94
	v_pk_mul_f32 v[84:85], v[84:85], v[150:151] op_sel_hi:[1,0]
	v_max_f32_e32 v0, 0, v86
	v_max_f32_e32 v86, 0, v87
	v_max_f32_e32 v87, 0, v88
	v_max_f32_e32 v88, 0, v89
	v_mul_f32_e32 v89, v82, v82
	v_max_f32_e32 v82, 0, v83
	v_mul_f32_e32 v95, v95, v95
	v_mul_f32_e32 v96, v96, v96
	v_cvt_pk_bf16_f32 v91, v95, v96
	v_cvt_pk_bf16_f32 v92, v97, v100
	v_cvt_pk_bf16_f32 v93, v101, v93
	v_pk_mul_f32 v[74:75], v[74:75], v[156:157] op_sel_hi:[1,0]
	v_mul_f32_e32 v0, v0, v0
	v_mul_f32_e32 v238, v82, v82
	v_max_f32_e32 v82, 0, v84
	v_mul_f32_e32 v239, v82, v82
	v_max_f32_e32 v82, 0, v85
	v_mul_f32_e32 v86, v86, v86
	v_mul_f32_e32 v85, v82, v82
	v_cvt_pk_bf16_f32 v82, v0, v86
	v_pk_mul_f32 v[80:81], v[80:81], v[156:157] op_sel_hi:[1,0]
	v_pk_mul_f32 v[78:79], v[78:79], v[156:157] op_sel_hi:[1,0]
	v_max_f32_e32 v74, 0, v74
	v_mul_f32_e32 v87, v87, v87
	v_mul_f32_e32 v88, v88, v88
	v_cvt_pk_bf16_f32 v83, v87, v88
	v_cvt_pk_bf16_f32 v84, v89, v238
	v_cvt_pk_bf16_f32 v85, v239, v85
	v_mov_b32_e32 v208, v90
	v_mov_b32_e32 v209, v91
	v_mov_b32_e32 v238, v92
	v_mov_b32_e32 v239, v93
	v_mov_b32_dpp v90, v82 row_ror:8 row_mask:0xf bank_mask:0xc
	v_mov_b32_dpp v91, v83 row_ror:8 row_mask:0xf bank_mask:0xc
	v_mov_b32_dpp v92, v84 row_ror:8 row_mask:0xf bank_mask:0xc
	v_mov_b32_dpp v93, v85 row_ror:8 row_mask:0xf bank_mask:0xc
	v_mov_b32_dpp v82, v208 row_ror:8 row_mask:0xf bank_mask:0x3
	v_mov_b32_dpp v83, v209 row_ror:8 row_mask:0xf bank_mask:0x3
	v_mov_b32_dpp v84, v238 row_ror:8 row_mask:0xf bank_mask:0x3
	v_mov_b32_dpp v85, v239 row_ror:8 row_mask:0xf bank_mask:0x3
	global_store_dwordx4 v[98:99], v[90:93], off
	v_lshl_add_u64 v[208:209], v[98:99], 0, s[100:101]
	global_store_dwordx4 v[208:209], v[82:85], off
	v_pk_mul_f32 v[76:77], v[76:77], v[156:157] op_sel_hi:[1,0]
	v_max_f32_e32 v0, 0, v78
	v_or_b32_e32 v82, 48, v148
	v_max_f32_e32 v78, 0, v79
	v_max_f32_e32 v79, 0, v80
	v_max_f32_e32 v80, 0, v81
	v_mul_f32_e32 v81, v74, v74
	v_max_f32_e32 v74, 0, v75
	v_ashrrev_i32_e32 v83, 31, v82
	v_mul_f32_e32 v84, v74, v74
	v_max_f32_e32 v74, 0, v76
	v_pk_mul_f32 v[66:67], v[66:67], v[156:157] op_sel_hi:[1,0]
	v_lshlrev_b64 v[82:83], 14, v[82:83]
	v_mul_f32_e32 v0, v0, v0
	v_mul_f32_e32 v85, v74, v74
	v_max_f32_e32 v74, 0, v77
	v_pk_mul_f32 v[72:73], v[72:73], v[156:157] op_sel_hi:[1,0]
	v_pk_mul_f32 v[70:71], v[70:71], v[156:157] op_sel_hi:[1,0]
	v_max_f32_e32 v66, 0, v66
	v_lshl_add_u64 v[82:83], v[172:173], 0, v[82:83]
	v_mul_f32_e32 v78, v78, v78
	v_mul_f32_e32 v77, v74, v74
	v_cvt_pk_bf16_f32 v74, v0, v78
	v_pk_mul_f32 v[68:69], v[68:69], v[156:157] op_sel_hi:[1,0]
	v_max_f32_e32 v0, 0, v70
	v_max_f32_e32 v70, 0, v71
	v_max_f32_e32 v71, 0, v72
	v_max_f32_e32 v72, 0, v73
	v_mul_f32_e32 v73, v66, v66
	v_max_f32_e32 v66, 0, v67
	v_mul_f32_e32 v79, v79, v79
	v_mul_f32_e32 v80, v80, v80
	v_cvt_pk_bf16_f32 v75, v79, v80
	v_cvt_pk_bf16_f32 v76, v81, v84
	v_cvt_pk_bf16_f32 v77, v85, v77
	v_pk_mul_f32 v[58:59], v[58:59], v[154:155] op_sel_hi:[1,0]
	v_mul_f32_e32 v0, v0, v0
	v_mul_f32_e32 v238, v66, v66
	v_max_f32_e32 v66, 0, v68
	v_mul_f32_e32 v239, v66, v66
	v_max_f32_e32 v66, 0, v69
	v_pk_mul_f32 v[64:65], v[64:65], v[154:155] op_sel_hi:[1,0]
	v_pk_mul_f32 v[62:63], v[62:63], v[154:155] op_sel_hi:[1,0]
	v_max_f32_e32 v58, 0, v58
	v_mul_f32_e32 v70, v70, v70
	v_mul_f32_e32 v71, v71, v71
	v_mul_f32_e32 v72, v72, v72
	v_mul_f32_e32 v69, v66, v66
	v_cvt_pk_bf16_f32 v66, v0, v70
	v_cvt_pk_bf16_f32 v67, v71, v72
	v_cvt_pk_bf16_f32 v68, v73, v238
	v_pk_mul_f32 v[60:61], v[60:61], v[154:155] op_sel_hi:[1,0]
	v_max_f32_e32 v0, 0, v62
	v_max_f32_e32 v62, 0, v63
	v_max_f32_e32 v63, 0, v64
	v_max_f32_e32 v64, 0, v65
	v_mul_f32_e32 v65, v58, v58
	v_max_f32_e32 v58, 0, v59
	v_cvt_pk_bf16_f32 v69, v239, v69
	v_mov_b32_e32 v208, v74
	v_mov_b32_e32 v209, v75
	v_mov_b32_e32 v238, v76
	v_mov_b32_e32 v239, v77
	v_mov_b32_dpp v74, v66 row_ror:8 row_mask:0xf bank_mask:0xc
	v_mov_b32_dpp v75, v67 row_ror:8 row_mask:0xf bank_mask:0xc
	v_mov_b32_dpp v76, v68 row_ror:8 row_mask:0xf bank_mask:0xc
	v_mov_b32_dpp v77, v69 row_ror:8 row_mask:0xf bank_mask:0xc
	v_mov_b32_dpp v66, v208 row_ror:8 row_mask:0xf bank_mask:0x3
	v_mov_b32_dpp v67, v209 row_ror:8 row_mask:0xf bank_mask:0x3
	v_mov_b32_dpp v68, v238 row_ror:8 row_mask:0xf bank_mask:0x3
	v_mov_b32_dpp v69, v239 row_ror:8 row_mask:0xf bank_mask:0x3
	global_store_dwordx4 v[82:83], v[74:77], off
	v_lshl_add_u64 v[208:209], v[82:83], 0, s[100:101]
	global_store_dwordx4 v[208:209], v[66:69], off
	v_mul_f32_e32 v62, v62, v62
	s_mov_b32 s7, 0x200000
	v_mul_f32_e32 v68, v58, v58
	v_max_f32_e32 v58, 0, v60
	v_mul_f32_e32 v69, v58, v58
	v_max_f32_e32 v58, 0, v61
	v_pk_mul_f32 v[50:51], v[50:51], v[154:155] op_sel_hi:[1,0]
	v_mul_f32_e32 v0, v0, v0
	v_mul_f32_e32 v63, v63, v63
	v_mul_f32_e32 v61, v58, v58
	v_cvt_pk_bf16_f32 v58, v0, v62
	v_add_co_u32_e32 v62, vcc, s7, v164
	v_pk_mul_f32 v[56:57], v[56:57], v[154:155] op_sel_hi:[1,0]
	v_pk_mul_f32 v[54:55], v[54:55], v[154:155] op_sel_hi:[1,0]
	v_max_f32_e32 v50, 0, v50
	v_mul_f32_e32 v64, v64, v64
	v_cvt_pk_bf16_f32 v59, v63, v64
	v_addc_co_u32_e32 v63, vcc, 0, v165, vcc
	v_pk_mul_f32 v[52:53], v[52:53], v[154:155] op_sel_hi:[1,0]
	v_max_f32_e32 v0, 0, v54
	v_max_f32_e32 v54, 0, v55
	v_max_f32_e32 v55, 0, v56
	v_max_f32_e32 v56, 0, v57
	v_mul_f32_e32 v57, v50, v50
	v_max_f32_e32 v50, 0, v51
	v_cvt_pk_bf16_f32 v60, v65, v68
	v_cvt_pk_bf16_f32 v61, v69, v61
	v_pk_mul_f32 v[42:43], v[42:43], v[160:161] op_sel_hi:[1,0]
	v_mul_f32_e32 v0, v0, v0
	v_mul_f32_e32 v238, v50, v50
	v_max_f32_e32 v50, 0, v52
	v_mul_f32_e32 v239, v50, v50
	v_max_f32_e32 v50, 0, v53
	v_pk_mul_f32 v[48:49], v[48:49], v[160:161] op_sel_hi:[1,0]
	v_pk_mul_f32 v[46:47], v[46:47], v[160:161] op_sel_hi:[1,0]
	v_max_f32_e32 v42, 0, v42
	v_lshl_add_u64 v[66:67], v[164:165], 0, s[50:51]
	v_mul_f32_e32 v54, v54, v54
	v_mul_f32_e32 v55, v55, v55
	v_mul_f32_e32 v56, v56, v56
	v_mul_f32_e32 v53, v50, v50
	v_cvt_pk_bf16_f32 v50, v0, v54
	v_cvt_pk_bf16_f32 v51, v55, v56
	v_cvt_pk_bf16_f32 v52, v57, v238
	v_pk_mul_f32 v[44:45], v[44:45], v[160:161] op_sel_hi:[1,0]
	v_max_f32_e32 v0, 0, v46
	v_max_f32_e32 v46, 0, v47
	v_max_f32_e32 v47, 0, v48
	v_max_f32_e32 v48, 0, v49
	v_mul_f32_e32 v49, v42, v42
	v_max_f32_e32 v42, 0, v43
	v_cvt_pk_bf16_f32 v53, v239, v53
	v_mov_b32_e32 v208, v58
	v_mov_b32_e32 v209, v59
	v_mov_b32_e32 v238, v60
	v_mov_b32_e32 v239, v61
	v_mov_b32_dpp v58, v50 row_ror:8 row_mask:0xf bank_mask:0xc
	v_mov_b32_dpp v59, v51 row_ror:8 row_mask:0xf bank_mask:0xc
	v_mov_b32_dpp v60, v52 row_ror:8 row_mask:0xf bank_mask:0xc
	v_mov_b32_dpp v61, v53 row_ror:8 row_mask:0xf bank_mask:0xc
	v_mov_b32_dpp v50, v208 row_ror:8 row_mask:0xf bank_mask:0x3
	v_mov_b32_dpp v51, v209 row_ror:8 row_mask:0xf bank_mask:0x3
	v_mov_b32_dpp v52, v238 row_ror:8 row_mask:0xf bank_mask:0x3
	v_mov_b32_dpp v53, v239 row_ror:8 row_mask:0xf bank_mask:0x3
	global_store_dwordx4 v[62:63], v[58:61], off
	v_lshl_add_u64 v[208:209], v[62:63], 0, s[100:101]
	global_store_dwordx4 v[208:209], v[50:53], off
	v_mul_f32_e32 v46, v46, v46
	s_mov_b32 s7, 0x240000
	v_mul_f32_e32 v52, v42, v42
	v_max_f32_e32 v42, 0, v44
	v_mul_f32_e32 v53, v42, v42
	v_max_f32_e32 v42, 0, v45
	v_pk_mul_f32 v[34:35], v[34:35], v[160:161] op_sel_hi:[1,0]
	v_mul_f32_e32 v0, v0, v0
	v_mul_f32_e32 v47, v47, v47
	v_mul_f32_e32 v45, v42, v42
	v_cvt_pk_bf16_f32 v42, v0, v46
	v_add_co_u32_e32 v46, vcc, s7, v164
	v_pk_mul_f32 v[40:41], v[40:41], v[160:161] op_sel_hi:[1,0]
	v_pk_mul_f32 v[38:39], v[38:39], v[160:161] op_sel_hi:[1,0]
	v_max_f32_e32 v34, 0, v34
	v_mul_f32_e32 v48, v48, v48
	v_cvt_pk_bf16_f32 v43, v47, v48
	v_addc_co_u32_e32 v47, vcc, 0, v165, vcc
	v_pk_mul_f32 v[36:37], v[36:37], v[160:161] op_sel_hi:[1,0]
	v_max_f32_e32 v0, 0, v38
	v_max_f32_e32 v38, 0, v39
	v_max_f32_e32 v39, 0, v40
	v_max_f32_e32 v40, 0, v41
	v_mul_f32_e32 v41, v34, v34
	v_max_f32_e32 v34, 0, v35
	v_cvt_pk_bf16_f32 v44, v49, v52
	v_cvt_pk_bf16_f32 v45, v53, v45
	v_pk_mul_f32 v[26:27], v[26:27], v[158:159] op_sel_hi:[1,0]
	s_mov_b64 s[10:11], 0x240000
	v_mul_f32_e32 v238, v34, v34
	v_max_f32_e32 v34, 0, v36
	v_mul_f32_e32 v0, v0, v0
	v_mul_f32_e32 v239, v34, v34
	v_max_f32_e32 v34, 0, v37
	v_pk_mul_f32 v[32:33], v[32:33], v[158:159] op_sel_hi:[1,0]
	v_pk_mul_f32 v[30:31], v[30:31], v[158:159] op_sel_hi:[1,0]
	v_max_f32_e32 v26, 0, v26
	v_lshl_add_u64 v[50:51], v[164:165], 0, s[10:11]
	v_mul_f32_e32 v38, v38, v38
	v_mul_f32_e32 v39, v39, v39
	v_mul_f32_e32 v40, v40, v40
	v_mul_f32_e32 v37, v34, v34
	v_cvt_pk_bf16_f32 v34, v0, v38
	v_cvt_pk_bf16_f32 v35, v39, v40
	v_cvt_pk_bf16_f32 v36, v41, v238
	v_pk_mul_f32 v[28:29], v[28:29], v[158:159] op_sel_hi:[1,0]
	v_max_f32_e32 v0, 0, v30
	v_max_f32_e32 v30, 0, v31
	v_max_f32_e32 v31, 0, v32
	v_max_f32_e32 v32, 0, v33
	v_mul_f32_e32 v33, v26, v26
	v_max_f32_e32 v26, 0, v27
	v_cvt_pk_bf16_f32 v37, v239, v37
	v_mov_b32_e32 v208, v42
	v_mov_b32_e32 v209, v43
	v_mov_b32_e32 v238, v44
	v_mov_b32_e32 v239, v45
	v_mov_b32_dpp v42, v34 row_ror:8 row_mask:0xf bank_mask:0xc
	v_mov_b32_dpp v43, v35 row_ror:8 row_mask:0xf bank_mask:0xc
	v_mov_b32_dpp v44, v36 row_ror:8 row_mask:0xf bank_mask:0xc
	v_mov_b32_dpp v45, v37 row_ror:8 row_mask:0xf bank_mask:0xc
	v_mov_b32_dpp v34, v208 row_ror:8 row_mask:0xf bank_mask:0x3
	v_mov_b32_dpp v35, v209 row_ror:8 row_mask:0xf bank_mask:0x3
	v_mov_b32_dpp v36, v238 row_ror:8 row_mask:0xf bank_mask:0x3
	v_mov_b32_dpp v37, v239 row_ror:8 row_mask:0xf bank_mask:0x3
	global_store_dwordx4 v[46:47], v[42:45], off
	v_lshl_add_u64 v[208:209], v[46:47], 0, s[100:101]
	global_store_dwordx4 v[208:209], v[34:37], off
	v_mul_f32_e32 v30, v30, v30
	s_mov_b32 s7, 0x280000
	v_mul_f32_e32 v36, v26, v26
	v_max_f32_e32 v26, 0, v28
	v_mul_f32_e32 v37, v26, v26
	v_max_f32_e32 v26, 0, v29
	v_pk_mul_f32 v[18:19], v[18:19], v[158:159] op_sel_hi:[1,0]
	v_mul_f32_e32 v0, v0, v0
	v_mul_f32_e32 v31, v31, v31
	v_mul_f32_e32 v29, v26, v26
	v_cvt_pk_bf16_f32 v26, v0, v30
	v_add_co_u32_e32 v30, vcc, s7, v164
	v_pk_mul_f32 v[24:25], v[24:25], v[158:159] op_sel_hi:[1,0]
	v_pk_mul_f32 v[22:23], v[22:23], v[158:159] op_sel_hi:[1,0]
	v_max_f32_e32 v18, 0, v18
	v_mul_f32_e32 v32, v32, v32
	v_cvt_pk_bf16_f32 v27, v31, v32
	v_addc_co_u32_e32 v31, vcc, 0, v165, vcc
	v_pk_mul_f32 v[20:21], v[20:21], v[158:159] op_sel_hi:[1,0]
	v_max_f32_e32 v0, 0, v22
	v_max_f32_e32 v22, 0, v23
	v_max_f32_e32 v23, 0, v24
	v_max_f32_e32 v24, 0, v25
	v_mul_f32_e32 v25, v18, v18
	v_max_f32_e32 v18, 0, v19
	v_cvt_pk_bf16_f32 v28, v33, v36
	v_cvt_pk_bf16_f32 v29, v37, v29
	v_pk_mul_f32 v[10:11], v[10:11], v[162:163] op_sel_hi:[1,0]
	s_mov_b64 s[10:11], 0x280000
	v_mul_f32_e32 v238, v18, v18
	v_max_f32_e32 v18, 0, v20
	v_mul_f32_e32 v0, v0, v0
	v_mul_f32_e32 v239, v18, v18
	v_max_f32_e32 v18, 0, v21
	v_pk_mul_f32 v[16:17], v[16:17], v[162:163] op_sel_hi:[1,0]
	v_pk_mul_f32 v[14:15], v[14:15], v[162:163] op_sel_hi:[1,0]
	v_max_f32_e32 v10, 0, v10
	v_lshl_add_u64 v[34:35], v[164:165], 0, s[10:11]
	v_mul_f32_e32 v22, v22, v22
	v_mul_f32_e32 v23, v23, v23
	v_mul_f32_e32 v24, v24, v24
	v_mul_f32_e32 v21, v18, v18
	v_cvt_pk_bf16_f32 v18, v0, v22
	v_cvt_pk_bf16_f32 v19, v23, v24
	v_cvt_pk_bf16_f32 v20, v25, v238
	v_pk_mul_f32 v[12:13], v[12:13], v[162:163] op_sel_hi:[1,0]
	v_max_f32_e32 v0, 0, v14
	v_max_f32_e32 v14, 0, v15
	v_max_f32_e32 v15, 0, v16
	v_max_f32_e32 v16, 0, v17
	v_mul_f32_e32 v17, v10, v10
	v_max_f32_e32 v10, 0, v11
	v_cvt_pk_bf16_f32 v21, v239, v21
	v_mov_b32_e32 v208, v26
	v_mov_b32_e32 v209, v27
	v_mov_b32_e32 v238, v28
	v_mov_b32_e32 v239, v29
	v_mov_b32_dpp v26, v18 row_ror:8 row_mask:0xf bank_mask:0xc
	v_mov_b32_dpp v27, v19 row_ror:8 row_mask:0xf bank_mask:0xc
	v_mov_b32_dpp v28, v20 row_ror:8 row_mask:0xf bank_mask:0xc
	v_mov_b32_dpp v29, v21 row_ror:8 row_mask:0xf bank_mask:0xc
	v_mov_b32_dpp v18, v208 row_ror:8 row_mask:0xf bank_mask:0x3
	v_mov_b32_dpp v19, v209 row_ror:8 row_mask:0xf bank_mask:0x3
	v_mov_b32_dpp v20, v238 row_ror:8 row_mask:0xf bank_mask:0x3
	v_mov_b32_dpp v21, v239 row_ror:8 row_mask:0xf bank_mask:0x3
	global_store_dwordx4 v[30:31], v[26:29], off
	v_lshl_add_u64 v[208:209], v[30:31], 0, s[100:101]
	global_store_dwordx4 v[208:209], v[18:21], off
	v_mul_f32_e32 v0, v0, v0
	v_mul_f32_e32 v14, v14, v14
	v_mul_f32_e32 v20, v10, v10
	v_max_f32_e32 v10, 0, v12
	v_mul_f32_e32 v21, v10, v10
	v_max_f32_e32 v10, 0, v13
	s_mov_b32 s7, 0x2c0000
	v_pk_mul_f32 v[4:5], v[4:5], v[162:163] op_sel_hi:[1,0]
	v_pk_mul_f32 v[2:3], v[2:3], v[162:163] op_sel_hi:[1,0]
	v_pk_mul_f32 v[6:7], v[6:7], v[162:163] op_sel_hi:[1,0]
	v_mul_f32_e32 v15, v15, v15
	v_mul_f32_e32 v13, v10, v10
	v_cvt_pk_bf16_f32 v10, v0, v14
	v_add_co_u32_e32 v14, vcc, s7, v164
	v_pk_mul_f32 v[8:9], v[8:9], v[162:163] op_sel_hi:[1,0]
	v_max_f32_e32 v0, 0, v2
	v_max_f32_e32 v2, 0, v3
	v_max_f32_e32 v3, 0, v4
	v_max_f32_e32 v4, 0, v5
	v_max_f32_e32 v5, 0, v6
	s_mov_b64 s[10:11], 0x2c0000
	v_mul_f32_e32 v16, v16, v16
	v_cvt_pk_bf16_f32 v11, v15, v16
	v_addc_co_u32_e32 v15, vcc, 0, v165, vcc
	v_mul_f32_e32 v2, v2, v2
	v_mul_f32_e32 v3, v3, v3
	v_mul_f32_e32 v4, v4, v4
	v_mul_f32_e32 v5, v5, v5
	v_max_f32_e32 v6, 0, v7
	v_max_f32_e32 v7, 0, v8
	v_max_f32_e32 v8, 0, v9
	v_lshl_add_u64 v[18:19], v[164:165], 0, s[10:11]
	v_cvt_pk_bf16_f32 v12, v17, v20
	v_cvt_pk_bf16_f32 v13, v21, v13
	v_mul_f32_e32 v0, v0, v0
	v_mul_f32_e32 v6, v6, v6
	v_mul_f32_e32 v7, v7, v7
	v_mul_f32_e32 v8, v8, v8
	v_cvt_pk_bf16_f32 v2, v0, v2
	v_cvt_pk_bf16_f32 v3, v3, v4
	v_cvt_pk_bf16_f32 v4, v5, v6
	v_cvt_pk_bf16_f32 v5, v7, v8
	s_mov_b64 s[10:11], -1
	s_andn2_b64 vcc, exec, s[4:5]
	v_mov_b32_e32 v208, v10
	v_mov_b32_e32 v209, v11
	v_mov_b32_e32 v238, v12
	v_mov_b32_e32 v239, v13
	v_mov_b32_dpp v10, v2 row_ror:8 row_mask:0xf bank_mask:0xc
	v_mov_b32_dpp v11, v3 row_ror:8 row_mask:0xf bank_mask:0xc
	v_mov_b32_dpp v12, v4 row_ror:8 row_mask:0xf bank_mask:0xc
	v_mov_b32_dpp v13, v5 row_ror:8 row_mask:0xf bank_mask:0xc
	v_mov_b32_dpp v2, v208 row_ror:8 row_mask:0xf bank_mask:0x3
	v_mov_b32_dpp v3, v209 row_ror:8 row_mask:0xf bank_mask:0x3
	v_mov_b32_dpp v4, v238 row_ror:8 row_mask:0xf bank_mask:0x3
	v_mov_b32_dpp v5, v239 row_ror:8 row_mask:0xf bank_mask:0x3
	global_store_dwordx4 v[14:15], v[10:13], off
	v_lshl_add_u64 v[208:209], v[14:15], 0, s[100:101]
	global_store_dwordx4 v[208:209], v[2:5], off
	s_cbranch_vccnz .LBB0_1160
	s_andn2_b64 vcc, exec, s[0:1]
	s_cbranch_vccnz .LBB0_1159
	s_barrier
	s_branch .LBB0_1159

	.amdhsa_kernel _Z10fwd_kernel6Params
		.amdhsa_group_segment_fixed_size 0
		.amdhsa_private_segment_fixed_size 0
		.amdhsa_kernarg_size 496
		.amdhsa_user_sgpr_count 2
		.amdhsa_user_sgpr_dispatch_ptr 0
		.amdhsa_user_sgpr_queue_ptr 0
		.amdhsa_user_sgpr_kernarg_segment_ptr 1
		.amdhsa_user_sgpr_dispatch_id 0
		.amdhsa_user_sgpr_kernarg_preload_length 0
		.amdhsa_user_sgpr_kernarg_preload_offset 0
		.amdhsa_user_sgpr_private_segment_size 0
		.amdhsa_uses_dynamic_stack 0
		.amdhsa_enable_private_segment 0
		.amdhsa_system_sgpr_workgroup_id_x 1
		.amdhsa_system_sgpr_workgroup_id_y 0
		.amdhsa_system_sgpr_workgroup_id_z 0
		.amdhsa_system_sgpr_workgroup_info 0
		.amdhsa_system_vgpr_workitem_id 0
		.amdhsa_next_free_vgpr 256
		.amdhsa_next_free_sgpr 102
		.amdhsa_accum_offset 256
		.amdhsa_reserve_vcc 1
		.amdhsa_float_round_mode_32 0
		.amdhsa_float_round_mode_16_64 0
		.amdhsa_float_denorm_mode_32 3
		.amdhsa_float_denorm_mode_16_64 3
		.amdhsa_dx10_clamp 1
		.amdhsa_ieee_mode 1
		.amdhsa_fp16_overflow 0
		.amdhsa_tg_split 0
		.amdhsa_exception_fp_ieee_invalid_op 0
		.amdhsa_exception_fp_denorm_src 0
		.amdhsa_exception_fp_ieee_div_zero 0
		.amdhsa_exception_fp_ieee_overflow 0
		.amdhsa_exception_fp_ieee_underflow 0
		.amdhsa_exception_fp_ieee_inexact 0
		.amdhsa_exception_int_div_zero 0
	.end_amdhsa_kernel

amdhsa.kernels:
  - .agpr_count:     0
    .args:
      - .offset:         0
        .size:           240
        .value_kind:     by_value
      - .offset:         240
        .size:           4
        .value_kind:     hidden_block_count_x
      - .offset:         244
        .size:           4
        .value_kind:     hidden_block_count_y
      - .offset:         248
        .size:           4
        .value_kind:     hidden_block_count_z
      - .offset:         252
        .size:           2
        .value_kind:     hidden_group_size_x
      - .offset:         254
        .size:           2
        .value_kind:     hidden_group_size_y
      - .offset:         256
        .size:           2
        .value_kind:     hidden_group_size_z
      - .offset:         258
        .size:           2
        .value_kind:     hidden_remainder_x
      - .offset:         260
        .size:           2
        .value_kind:     hidden_remainder_y
      - .offset:         262
        .size:           2
        .value_kind:     hidden_remainder_z
      - .offset:         280
        .size:           8
        .value_kind:     hidden_global_offset_x
      - .offset:         288
        .size:           8
        .value_kind:     hidden_global_offset_y
      - .offset:         296
        .size:           8
        .value_kind:     hidden_global_offset_z
      - .offset:         304
        .size:           2
        .value_kind:     hidden_grid_dims
      - .offset:         360
        .size:           4
        .value_kind:     hidden_dynamic_lds_size
    .group_segment_fixed_size: 0
    .kernarg_segment_align: 8
    .kernarg_segment_size: 496
    .language:       OpenCL C
    .language_version:
      - 2
      - 0
    .max_flat_workgroup_size: 512
    .name:           _Z10fwd_kernel6Params
    .private_segment_fixed_size: 0
    .sgpr_count:     108
    .sgpr_spill_count: 73
    .symbol:         _Z10fwd_kernel6Params.kd
    .uniform_work_group_size: 1
    .uses_dynamic_stack: false
    .vgpr_count:     256
    .vgpr_spill_count: 0
    .wavefront_size: 64
